# lever 4: static s_setprio 1 for waves 4-7 in the three attention tile loops, per-cluster prio flips deleted there
# speedup vs baseline: 1.0000x; 1.0000x over previous
; #define LAS __attribute__((address_space(3)))
; template <int D, int DV, int MODE, int NMAP, int KT> ...
;     ...
;         __syncthreads();
;         const int cur = (kt & 1) * BUF_BYTES;
;         if (kt + 1 < nkt) { AT_STORE(((kt + 1) & 1) * BUF_BYTES); if (kt + 2 < nkt) AT_LOAD(kt + 2); }
;         if (MODE == 0 || kt * KT <= rowmin + 15) {
;             const LAS bf16_t* Ks = (const LAS bf16_t*)(lds + cur); const LAS bf16_t* Vt = (const LAS bf16_t*)(lds + cur + KS_BYTES);
;             const bool diag = (MODE != 0) && (kt * KT + KT - 1 > rowmin);
;             bf16x8 pb[NMAP][KK2];
;             f32x4 sall[NMAP][NB];
; #pragma unroll
;             for (int mp = 0; mp < NMAP; ++mp) {
;                 f32x4 (&s)[NB] = sall[mp];
;                 constexpr int KD = D / 32, NBB = (KD >= 8) ? 1 : (8 / KD), NSB = NB / NBB;
;                 bf16x8 kfr[2][NBB][KD];
;     ...
;                 AT_SLOAD(0, 0);
; #pragma unroll
;                 for (int bi = 0; bi < NSB; ++bi) {
;                     if (bi + 1 < NSB) AT_SLOAD(bi + 1, (bi + 1) & 1);
;                     __builtin_amdgcn_sched_barrier(0);
;                     __builtin_amdgcn_s_setprio(1);
; #pragma unroll
;                     for (int x_ = 0; x_ < NBB; ++x_) { const int nb = bi * NBB + x_;
;                         s[nb] = __builtin_amdgcn_mfma_f32_16x16x32_bf16(kfr[bi & 1][x_][0], qf[mp][0], (f32x4){0.f, 0.f, 0.f, 0.f}, 0, 0, 0);
; #pragma unroll
;                         for (int kk = 1; kk < KD; ++kk) s[nb] = __builtin_amdgcn_mfma_f32_16x16x32_bf16(kfr[bi & 1][x_][kk], qf[mp][kk], s[nb], 0, 0, 0); }
;                     __builtin_amdgcn_s_setprio(0);
;                     __builtin_amdgcn_sched_barrier(0);
;                 }
;     ...
;             }
; #pragma unroll
;             for (int mp = 0; mp < NMAP; ++mp) {
;                 f32x4 (&s)[NB] = sall[mp];
;                 if (MODE < 2) {
;                     if (diag) {
; #pragma unroll
;                         for (int nb = 0; nb < NB; ++nb)
; #pragma unroll
;                             for (int j = 0; j < 4; ++j) { if (kt * KT + nb * 16 + g4 * 4 + j > myrow) s[nb][j] = -INFINITY; }
;                     }
;                     float mx = fmaxf(fmaxf(s[0][0], s[0][1]), s[0][2]);
;                     mx = fmaxf(fmaxf(mx, s[0][3]), s[1][0]); mx = fmaxf(fmaxf(mx, s[1][1]), s[1][2]); mx = fmaxf(fmaxf(mx, s[1][3]), s[2][0]);
.LBB0_597:
	s_add_i32 s6, 0, 0x11400
	v_or_b32_e32 v130, 16, v160
	v_lshl_add_u32 v131, v158, 1, s6
	s_waitcnt vmcnt(0)
	v_add_u32_e32 v126, v131, v170
	v_add_u32_e32 v148, 0x2100, v126
	s_barrier
	ds_read_b128 v[98:101], v126
	ds_read_b128 v[102:105], v126 offset:64
	ds_read_b128 v[106:109], v126 offset:128
	ds_read_b128 v[110:113], v126 offset:192
	ds_read_b128 v[114:117], v126 offset:256
	ds_read_b128 v[118:121], v126 offset:320
	ds_read_b128 v[122:125], v126 offset:384
	ds_read_b128 v[126:129], v126 offset:448
	ds_read_b128 v[130:133], v148
	ds_read_b128 v[134:137], v148 offset:64
	ds_read_b128 v[138:141], v148 offset:128
	ds_read_b128 v[142:145], v148 offset:192
	ds_read_b128 v[150:153], v148 offset:256
	ds_read_b128 v[154:157], v148 offset:320
	ds_read_b128 v[160:163], v148 offset:384
	ds_read_b128 v[164:167], v148 offset:448
	s_waitcnt lgkmcnt(14)
	v_mfma_f32_16x16x32_bf16 v[98:101], v[98:101], v[66:69], 0
	v_mfma_f32_16x16x32_bf16 v[98:101], v[102:105], v[70:73], v[98:101]
	s_waitcnt lgkmcnt(13)
	v_mfma_f32_16x16x32_bf16 v[98:101], v[106:109], v[74:77], v[98:101]
	s_waitcnt lgkmcnt(12)
	v_mfma_f32_16x16x32_bf16 v[98:101], v[110:113], v[78:81], v[98:101]
	s_waitcnt lgkmcnt(11)
	v_mfma_f32_16x16x32_bf16 v[98:101], v[114:117], v[82:85], v[98:101]
	s_waitcnt lgkmcnt(10)
	v_mfma_f32_16x16x32_bf16 v[98:101], v[118:121], v[86:89], v[98:101]
	s_waitcnt lgkmcnt(9)
	v_mfma_f32_16x16x32_bf16 v[98:101], v[122:125], v[90:93], v[98:101]
	s_waitcnt lgkmcnt(8)
	v_mfma_f32_16x16x32_bf16 v[106:109], v[126:129], v[94:97], v[98:101]
	s_nop 4
	ds_read_b128 v[98:101], v148 offset:8448
	ds_read_b128 v[110:113], v148 offset:8512
	ds_read_b128 v[114:117], v148 offset:8576
	ds_read_b128 v[118:121], v148 offset:8640
	ds_read_b128 v[122:125], v148 offset:8704
	ds_read_b128 v[126:129], v148 offset:8768
	ds_read_b128 v[168:171], v148 offset:8832
	ds_read_b128 v[176:179], v148 offset:8896
	s_waitcnt lgkmcnt(14)
	v_mfma_f32_16x16x32_bf16 v[102:105], v[130:133], v[66:69], 0
	v_mfma_f32_16x16x32_bf16 v[102:105], v[134:137], v[70:73], v[102:105]
	s_waitcnt lgkmcnt(13)
	v_mfma_f32_16x16x32_bf16 v[102:105], v[138:141], v[74:77], v[102:105]
	s_waitcnt lgkmcnt(12)
	v_mfma_f32_16x16x32_bf16 v[102:105], v[142:145], v[78:81], v[102:105]
	s_waitcnt lgkmcnt(11)
	v_mfma_f32_16x16x32_bf16 v[102:105], v[150:153], v[82:85], v[102:105]
	s_waitcnt lgkmcnt(10)
	v_mfma_f32_16x16x32_bf16 v[102:105], v[154:157], v[86:89], v[102:105]
	s_waitcnt lgkmcnt(9)
	v_mfma_f32_16x16x32_bf16 v[102:105], v[160:163], v[90:93], v[102:105]
	s_waitcnt lgkmcnt(8)
	v_mfma_f32_16x16x32_bf16 v[102:105], v[164:167], v[94:97], v[102:105]
	ds_read_b128 v[130:133], v148 offset:16896
	ds_read_b128 v[134:137], v148 offset:16960
	ds_read_b128 v[138:141], v148 offset:17024
	ds_read_b128 v[142:145], v148 offset:17088
	ds_read_b128 v[150:153], v148 offset:17152
	ds_read_b128 v[154:157], v148 offset:17216
	ds_read_b128 v[160:163], v148 offset:17280
	ds_read_b128 v[164:167], v148 offset:17344
	s_waitcnt lgkmcnt(14)
	v_mfma_f32_16x16x32_bf16 v[98:101], v[98:101], v[66:69], 0
	v_mfma_f32_16x16x32_bf16 v[98:101], v[110:113], v[70:73], v[98:101]
	s_waitcnt lgkmcnt(13)
	v_mfma_f32_16x16x32_bf16 v[98:101], v[114:117], v[74:77], v[98:101]
	s_waitcnt lgkmcnt(12)
	v_mfma_f32_16x16x32_bf16 v[98:101], v[118:121], v[78:81], v[98:101]
	s_waitcnt lgkmcnt(11)
	v_mfma_f32_16x16x32_bf16 v[98:101], v[122:125], v[82:85], v[98:101]
	s_waitcnt lgkmcnt(10)
	v_mfma_f32_16x16x32_bf16 v[98:101], v[126:129], v[86:89], v[98:101]
	s_waitcnt lgkmcnt(9)
	v_mfma_f32_16x16x32_bf16 v[98:101], v[168:171], v[90:93], v[98:101]
	s_waitcnt lgkmcnt(8)
	v_mfma_f32_16x16x32_bf16 v[98:101], v[176:179], v[94:97], v[98:101]
	s_waitcnt lgkmcnt(7)
	v_mfma_f32_16x16x32_bf16 v[66:69], v[130:133], v[66:69], 0
	s_waitcnt lgkmcnt(6)
	v_mfma_f32_16x16x32_bf16 v[66:69], v[134:137], v[70:73], v[66:69]
	s_waitcnt lgkmcnt(5)
	v_mfma_f32_16x16x32_bf16 v[66:69], v[138:141], v[74:77], v[66:69]
	s_waitcnt lgkmcnt(4)
	v_mfma_f32_16x16x32_bf16 v[66:69], v[142:145], v[78:81], v[66:69]
	s_waitcnt lgkmcnt(3)
	v_mfma_f32_16x16x32_bf16 v[66:69], v[150:153], v[82:85], v[66:69]
	s_waitcnt lgkmcnt(2)
	v_mfma_f32_16x16x32_bf16 v[66:69], v[154:157], v[86:89], v[66:69]
	s_waitcnt lgkmcnt(1)
	v_mfma_f32_16x16x32_bf16 v[66:69], v[160:163], v[90:93], v[66:69]
	s_waitcnt lgkmcnt(0)
	v_mfma_f32_16x16x32_bf16 v[66:69], v[164:167], v[94:97], v[66:69]
	v_max_f32_e32 v70, v107, v107
	v_max_f32_e32 v71, v106, v106
	v_max_f32_e32 v70, v71, v70
	v_max3_f32 v70, v70, v108, v109
	v_max3_f32 v70, v70, v102, v103
	v_max3_f32 v70, v70, v104, v105
	v_max3_f32 v70, v70, v98, v99
	v_max3_f32 v70, v70, v100, v101
	v_max3_f32 v70, v70, v66, v67
	v_max3_f32 v70, v70, v68, v69
	v_mov_b32_e32 v71, v70
	s_nop 1
	v_permlane16_swap_b32_e32 v70, v71
	v_max_f32_e32 v71, v71, v71
	v_max_f32_e32 v70, v70, v70
	v_max_f32_e32 v70, v70, v71
	v_mov_b32_e32 v71, v70
	s_nop 1
	v_permlane32_swap_b32_e32 v70, v71
	v_max_f32_e32 v71, v71, v71
	v_max_f32_e32 v70, v70, v70
	v_max_f32_e32 v70, v70, v71
	v_mul_f32_e32 v70, 0x3db8aa3b, v70
	v_add_f32_e32 v71, 0x40c00000, v175
	v_cmp_gt_f32_e32 vcc, v70, v71
	s_cbranch_vccz .LBB0_607
; __device__ __forceinline__ unsigned cvt_pk_bf16(float lo, float hi) { unsigned r; asm volatile("v_cvt_pk_bf16_f32 %0, %1, %2" : "=v"(r) : "v"(lo), "v"(hi)); return r; }
; template <int D, int DV, int MODE, int NMAP, int KT> ...
;     ...
;                     if (__any(mx > m[mp] + 6.0f)) {
;                         const float mn = fmaxf(m[mp], mx); const float al = __builtin_amdgcn_exp2f(m[mp] - mn); m[mp] = mn; l[mp] *= al;
; #pragma unroll
;                         for (int cb = 0; cb < DV / 16; ++cb) o[mp][cb] = o[mp][cb] * al;
;                     }
;                     const float nm = -m[mp]; float ps = 0.f;
; #pragma unroll
;                     for (int nb = 0; nb < NB; ++nb)
; #pragma unroll
;                         for (int j = 0; j < 4; ++j) { const float p = __builtin_amdgcn_exp2f(fmaf(s[nb][j], sc, nm)); ps += p; s[nb][j] = p; }
;                     l[mp] += ps;
;                 } else {
;                     const float rowf = __builtin_amdgcn_exp2f(l2g * (float)(myrow - kt * KT));
; #pragma unroll
;                     for (int nb = 0; nb < NB; ++nb)
; #pragma unroll
;                         for (int j = 0; j < 4; ++j) { float p = s[nb][j] * (rowf * ck[nb][j]); if (diag && (kt * KT + nb * 16 + g4 * 4 + j > myrow)) p = 0.f; s[nb][j] = p; }
;                 }
; #pragma unroll
;                 for (int kk = 0; kk < KK2; ++kk) { u32x4 wv; wv.x = cvt_pk_bf16(s[2 * kk][0], s[2 * kk][1]); wv.y = cvt_pk_bf16(s[2 * kk][2], s[2 * kk][3]);
;                     wv.z = cvt_pk_bf16(s[2 * kk + 1][0], s[2 * kk + 1][1]); wv.w = cvt_pk_bf16(s[2 * kk + 1][2], s[2 * kk + 1][3]); pb[mp][kk] = __builtin_bit_cast(bf16x8, wv); }
;             }
;             {
;                 constexpr int CBB = 4, NCB = (DV / 16) / CBB, NVB = KK2 * NCB;
;                 bf16x8 vfr[2][CBB];
;     ...
;                 AT_VLOAD(0, 0);
; #pragma unroll
;                 for (int b_ = 0; b_ < NVB; ++b_) {
;                     if (b_ + 1 < NVB) AT_VLOAD(b_ + 1, (b_ + 1) & 1);
	v_max_f32_e64 v70, -v70, -v70
	v_max_f32_e64 v71, -v175, -v175
	v_min_f32_e32 v70, v71, v70
	v_add_f32_e32 v71, v175, v70
	v_exp_f32_e32 v72, v71
	s_nop 0
	v_mul_f32_e32 v159, v159, v72
	v_pk_mul_f32 v[64:65], v[64:65], v[72:73] op_sel_hi:[1,0]
	v_pk_mul_f32 v[62:63], v[62:63], v[72:73] op_sel_hi:[1,0]
	v_pk_mul_f32 v[60:61], v[60:61], v[72:73] op_sel_hi:[1,0]
	v_pk_mul_f32 v[58:59], v[58:59], v[72:73] op_sel_hi:[1,0]
	v_pk_mul_f32 v[56:57], v[56:57], v[72:73] op_sel_hi:[1,0]
	v_pk_mul_f32 v[54:55], v[54:55], v[72:73] op_sel_hi:[1,0]
	v_pk_mul_f32 v[52:53], v[52:53], v[72:73] op_sel_hi:[1,0]
	v_pk_mul_f32 v[50:51], v[50:51], v[72:73] op_sel_hi:[1,0]
	v_pk_mul_f32 v[48:49], v[48:49], v[72:73] op_sel_hi:[1,0]
	v_pk_mul_f32 v[46:47], v[46:47], v[72:73] op_sel_hi:[1,0]
	v_pk_mul_f32 v[44:45], v[44:45], v[72:73] op_sel_hi:[1,0]
	v_pk_mul_f32 v[42:43], v[42:43], v[72:73] op_sel_hi:[1,0]
	v_pk_mul_f32 v[40:41], v[40:41], v[72:73] op_sel_hi:[1,0]
	v_pk_mul_f32 v[38:39], v[38:39], v[72:73] op_sel_hi:[1,0]
	v_pk_mul_f32 v[36:37], v[36:37], v[72:73] op_sel_hi:[1,0]
	v_pk_mul_f32 v[34:35], v[34:35], v[72:73] op_sel_hi:[1,0]
	v_pk_mul_f32 v[32:33], v[32:33], v[72:73] op_sel_hi:[1,0]
	v_pk_mul_f32 v[30:31], v[30:31], v[72:73] op_sel_hi:[1,0]
	v_pk_mul_f32 v[28:29], v[28:29], v[72:73] op_sel_hi:[1,0]
	v_pk_mul_f32 v[26:27], v[26:27], v[72:73] op_sel_hi:[1,0]
	v_pk_mul_f32 v[24:25], v[24:25], v[72:73] op_sel_hi:[1,0]
	v_pk_mul_f32 v[22:23], v[22:23], v[72:73] op_sel_hi:[1,0]
	v_pk_mul_f32 v[20:21], v[20:21], v[72:73] op_sel_hi:[1,0]
	v_pk_mul_f32 v[18:19], v[18:19], v[72:73] op_sel_hi:[1,0]
	v_pk_mul_f32 v[16:17], v[16:17], v[72:73] op_sel_hi:[1,0]
	v_pk_mul_f32 v[14:15], v[14:15], v[72:73] op_sel_hi:[1,0]
	v_pk_mul_f32 v[12:13], v[12:13], v[72:73] op_sel_hi:[1,0]
	v_pk_mul_f32 v[10:11], v[10:11], v[72:73] op_sel_hi:[1,0]
	v_pk_mul_f32 v[8:9], v[8:9], v[72:73] op_sel_hi:[1,0]
	v_pk_mul_f32 v[6:7], v[6:7], v[72:73] op_sel_hi:[1,0]
	v_pk_mul_f32 v[4:5], v[4:5], v[72:73] op_sel_hi:[1,0]
	v_pk_mul_f32 v[2:3], v[2:3], v[72:73] op_sel_hi:[1,0]
.LBB0_599:
	v_fmamk_f32 v71, v106, 0x3db8aa3b, v70
	v_exp_f32_e32 v71, v71
	v_fmamk_f32 v73, v107, 0x3db8aa3b, v70
	v_exp_f32_e32 v73, v73
	v_fmamk_f32 v74, v108, 0x3db8aa3b, v70
	v_exp_f32_e32 v74, v74
	v_fmamk_f32 v75, v109, 0x3db8aa3b, v70
	v_exp_f32_e32 v75, v75
	v_fmamk_f32 v76, v102, 0x3db8aa3b, v70
	v_add_f32_e32 v72, 0, v71
	v_exp_f32_e32 v76, v76
	v_fmamk_f32 v77, v103, 0x3db8aa3b, v70
	v_add_f32_e32 v72, v73, v72
	v_exp_f32_e32 v77, v77
	v_fmamk_f32 v78, v104, 0x3db8aa3b, v70
	v_add_f32_e32 v72, v74, v72
	v_exp_f32_e32 v78, v78
	v_fmamk_f32 v79, v105, 0x3db8aa3b, v70
	v_add_f32_e32 v72, v75, v72
	v_exp_f32_e32 v79, v79
	v_fmamk_f32 v80, v98, 0x3db8aa3b, v70
	v_add_f32_e32 v72, v76, v72
	v_exp_f32_e32 v80, v80
	v_fmamk_f32 v81, v99, 0x3db8aa3b, v70
	v_add_f32_e32 v72, v77, v72
	v_exp_f32_e32 v81, v81
	v_fmamk_f32 v82, v100, 0x3db8aa3b, v70
	v_add_f32_e32 v72, v78, v72
	v_exp_f32_e32 v82, v82
	v_fmamk_f32 v83, v101, 0x3db8aa3b, v70
	v_add_f32_e32 v72, v79, v72
	v_exp_f32_e32 v83, v83
	v_fmamk_f32 v66, v66, 0x3db8aa3b, v70
	v_add_f32_e32 v72, v80, v72
	v_exp_f32_e32 v84, v66
	v_fmamk_f32 v67, v67, 0x3db8aa3b, v70
	v_add_f32_e32 v72, v81, v72
	v_exp_f32_e32 v85, v67
	v_fmamk_f32 v67, v68, 0x3db8aa3b, v70
	v_add_f32_e32 v72, v82, v72
	v_exp_f32_e32 v86, v67
	v_fmac_f32_e32 v70, 0x3db8aa3b, v69
	v_add_f32_e32 v72, v83, v72
	v_exp_f32_e32 v69, v70
	v_add_f32_e32 v66, v84, v72
	v_add_f32_e32 v66, v85, v66
	v_readlane_b32 s6, v255, 12
	v_add_f32_e32 v66, v86, v66
	v_add_f32_e32 v66, v69, v66
	v_add3_u32 v107, s6, v158, v149
	v_add_u32_e32 v108, 0x800, v107
	v_add_u32_e32 v109, 0x1000, v107
	v_add_u32_e32 v110, 0x1800, v107
	v_add_u32_e32 v111, 0x2000, v107
	v_add_u32_e32 v112, 0x2800, v107
	v_add_u32_e32 v113, 0x3000, v107
	v_add_u32_e32 v114, 0x3800, v107
	v_add_f32_e32 v106, v159, v66
	v_cvt_pk_bf16_f32 v70, v71, v73
	v_cvt_pk_bf16_f32 v71, v74, v75
	v_cvt_pk_bf16_f32 v72, v76, v77
	v_cvt_pk_bf16_f32 v73, v78, v79
	v_cvt_pk_bf16_f32 v66, v80, v81
	v_cvt_pk_bf16_f32 v67, v82, v83
	v_cvt_pk_bf16_f32 v68, v84, v85
	v_cvt_pk_bf16_f32 v69, v86, v69
	ds_read_b64 v[74:75], v107
	ds_read_b64 v[76:77], v107 offset:32
	ds_read_b64 v[78:79], v108 offset:256
	ds_read_b64 v[80:81], v108 offset:288
	ds_read_b64 v[82:83], v109 offset:512
	ds_read_b64 v[84:85], v109 offset:544
	ds_read_b64 v[86:87], v110 offset:768
	ds_read_b64 v[88:89], v110 offset:800
	ds_read_b64 v[90:91], v111 offset:1024
	ds_read_b64 v[92:93], v111 offset:1056
	ds_read_b64 v[94:95], v112 offset:1280
	ds_read_b64 v[96:97], v112 offset:1312
	ds_read_b64 v[98:99], v113 offset:1536
	ds_read_b64 v[100:101], v113 offset:1568
	ds_read_b64 v[102:103], v114 offset:1792
	ds_read_b64 v[104:105], v114 offset:1824
	s_mov_b64 s[42:43], 0x800
	s_waitcnt lgkmcnt(14)
	v_mfma_f32_16x16x32_bf16 v[62:65], v[74:77], v[70:73], v[62:65]
	s_waitcnt lgkmcnt(12)
	v_mfma_f32_16x16x32_bf16 v[58:61], v[78:81], v[70:73], v[58:61]
	s_waitcnt lgkmcnt(10)
	v_mfma_f32_16x16x32_bf16 v[54:57], v[82:85], v[70:73], v[54:57]
	s_waitcnt lgkmcnt(8)
	v_mfma_f32_16x16x32_bf16 v[50:53], v[86:89], v[70:73], v[50:53]
	v_add_u32_e32 v115, 0x4800, v107
	v_add_u32_e32 v116, 0x5000, v107
	v_add_u32_e32 v117, 0x5800, v107
	v_add_u32_e32 v118, 0x6000, v107
	ds_read_b64 v[74:75], v115
	ds_read_b64 v[76:77], v115 offset:32
	ds_read_b64 v[78:79], v116 offset:256
	ds_read_b64 v[80:81], v116 offset:288
	ds_read_b64 v[82:83], v117 offset:512
	ds_read_b64 v[84:85], v117 offset:544
	ds_read_b64 v[86:87], v118 offset:768
	ds_read_b64 v[88:89], v118 offset:800
	s_waitcnt lgkmcnt(14)
; template <int D, int DV, int MODE, int NMAP, int KT> ...
;     ...
;                 for (int b_ = 0; b_ < NVB; ++b_) {
;                     if (b_ + 1 < NVB) AT_VLOAD(b_ + 1, (b_ + 1) & 1);
;                     __builtin_amdgcn_sched_barrier(0);
;                     const int kk_ = b_ / NCB, c0_ = (b_ % NCB) * CBB;
;                     __builtin_amdgcn_s_setprio(1);
; #pragma unroll
;                     for (int x_ = 0; x_ < CBB; ++x_)
; #pragma unroll
;                         for (int mp = 0; mp < NMAP; ++mp) o[mp][c0_ + x_] = __builtin_amdgcn_mfma_f32_16x16x32_bf16(vfr[b_ & 1][x_], pb[mp][kk_], o[mp][c0_ + x_], 0, 0, 0);
;                     __builtin_amdgcn_s_setprio(0);
;                     __builtin_amdgcn_sched_barrier(0);
;                 }
	v_mfma_f32_16x16x32_bf16 v[46:49], v[90:93], v[70:73], v[46:49]
	s_waitcnt lgkmcnt(12)
	v_mfma_f32_16x16x32_bf16 v[42:45], v[94:97], v[70:73], v[42:45]
	s_waitcnt lgkmcnt(10)
	v_mfma_f32_16x16x32_bf16 v[38:41], v[98:101], v[70:73], v[38:41]
	s_waitcnt lgkmcnt(8)
	v_mfma_f32_16x16x32_bf16 v[34:37], v[102:105], v[70:73], v[34:37]
	v_add_u32_e32 v119, 0x6800, v107
	v_add_u32_e32 v120, 0x7000, v107
	v_add_u32_e32 v121, 0x7800, v107
	v_add_u32_e32 v122, 0x8000, v107
	ds_read_b64 v[90:91], v119 offset:1024
	ds_read_b64 v[92:93], v119 offset:1056
	ds_read_b64 v[94:95], v120 offset:1280
	ds_read_b64 v[96:97], v120 offset:1312
	ds_read_b64 v[98:99], v121 offset:1536
	ds_read_b64 v[100:101], v121 offset:1568
	ds_read_b64 v[102:103], v122 offset:1792
	ds_read_b64 v[104:105], v122 offset:1824
	s_waitcnt lgkmcnt(14)
	v_mfma_f32_16x16x32_bf16 v[30:33], v[74:77], v[70:73], v[30:33]
	s_waitcnt lgkmcnt(12)
	v_mfma_f32_16x16x32_bf16 v[26:29], v[78:81], v[70:73], v[26:29]
	s_waitcnt lgkmcnt(10)
	v_mfma_f32_16x16x32_bf16 v[22:25], v[82:85], v[70:73], v[22:25]
	s_waitcnt lgkmcnt(8)
	v_mfma_f32_16x16x32_bf16 v[18:21], v[86:89], v[70:73], v[18:21]
	ds_read_b64 v[74:75], v107 offset:64
	ds_read_b64 v[76:77], v107 offset:96
	ds_read_b64 v[78:79], v108 offset:320
	ds_read_b64 v[80:81], v108 offset:352
	ds_read_b64 v[82:83], v109 offset:576
	ds_read_b64 v[84:85], v109 offset:608
	ds_read_b64 v[86:87], v110 offset:832
	ds_read_b64 v[88:89], v110 offset:864
	s_waitcnt lgkmcnt(14)
	v_mfma_f32_16x16x32_bf16 v[14:17], v[90:93], v[70:73], v[14:17]
	s_waitcnt lgkmcnt(12)
	v_mfma_f32_16x16x32_bf16 v[10:13], v[94:97], v[70:73], v[10:13]
	s_waitcnt lgkmcnt(10)
	v_mfma_f32_16x16x32_bf16 v[6:9], v[98:101], v[70:73], v[6:9]
	s_waitcnt lgkmcnt(8)
	v_mfma_f32_16x16x32_bf16 v[2:5], v[102:105], v[70:73], v[2:5]
	ds_read_b64 v[70:71], v111 offset:1088
	ds_read_b64 v[72:73], v111 offset:1120
	ds_read_b64 v[90:91], v112 offset:1344
	ds_read_b64 v[92:93], v112 offset:1376
	ds_read_b64 v[94:95], v113 offset:1600
	ds_read_b64 v[96:97], v113 offset:1632
	ds_read_b64 v[98:99], v114 offset:1856
	ds_read_b64 v[100:101], v114 offset:1888
	s_waitcnt lgkmcnt(14)
	v_mfma_f32_16x16x32_bf16 v[62:65], v[74:77], v[66:69], v[62:65]
	s_waitcnt lgkmcnt(12)
	v_mfma_f32_16x16x32_bf16 v[58:61], v[78:81], v[66:69], v[58:61]
	s_waitcnt lgkmcnt(10)
	v_mfma_f32_16x16x32_bf16 v[54:57], v[82:85], v[66:69], v[54:57]
	s_waitcnt lgkmcnt(8)
	v_mfma_f32_16x16x32_bf16 v[50:53], v[86:89], v[66:69], v[50:53]
	ds_read_b64 v[74:75], v115 offset:64
	ds_read_b64 v[76:77], v115 offset:96
	ds_read_b64 v[78:79], v116 offset:320
	ds_read_b64 v[80:81], v116 offset:352
	ds_read_b64 v[82:83], v117 offset:576
	ds_read_b64 v[84:85], v117 offset:608
	ds_read_b64 v[86:87], v118 offset:832
	ds_read_b64 v[88:89], v118 offset:864
	s_waitcnt lgkmcnt(14)
	v_mfma_f32_16x16x32_bf16 v[46:49], v[70:73], v[66:69], v[46:49]
	s_waitcnt lgkmcnt(12)
	v_mfma_f32_16x16x32_bf16 v[42:45], v[90:93], v[66:69], v[42:45]
	s_waitcnt lgkmcnt(10)
	v_mfma_f32_16x16x32_bf16 v[38:41], v[94:97], v[66:69], v[38:41]
	s_waitcnt lgkmcnt(8)
	v_mfma_f32_16x16x32_bf16 v[34:37], v[98:101], v[66:69], v[34:37]
	ds_read_b64 v[70:71], v119 offset:1088
	ds_read_b64 v[72:73], v119 offset:1120
	ds_read_b64 v[90:91], v120 offset:1344
	ds_read_b64 v[92:93], v120 offset:1376
	ds_read_b64 v[94:95], v121 offset:1600
	ds_read_b64 v[96:97], v121 offset:1632
	ds_read_b64 v[98:99], v122 offset:1856
	ds_read_b64 v[100:101], v122 offset:1888
	s_waitcnt lgkmcnt(14)
	v_mfma_f32_16x16x32_bf16 v[30:33], v[74:77], v[66:69], v[30:33]
	s_waitcnt lgkmcnt(12)
	v_mfma_f32_16x16x32_bf16 v[26:29], v[78:81], v[66:69], v[26:29]
	s_waitcnt lgkmcnt(10)
	v_mfma_f32_16x16x32_bf16 v[22:25], v[82:85], v[66:69], v[22:25]
	s_waitcnt lgkmcnt(8)
	v_mfma_f32_16x16x32_bf16 v[18:21], v[86:89], v[66:69], v[18:21]
	s_waitcnt lgkmcnt(6)
	v_mfma_f32_16x16x32_bf16 v[14:17], v[70:73], v[66:69], v[14:17]
	s_waitcnt lgkmcnt(4)
	v_mfma_f32_16x16x32_bf16 v[10:13], v[90:93], v[66:69], v[10:13]
	s_waitcnt lgkmcnt(2)
	v_mfma_f32_16x16x32_bf16 v[6:9], v[94:97], v[66:69], v[6:9]
	s_waitcnt lgkmcnt(0)
; __device__ __forceinline__ float xsum_rows(float v) { return xsum32(xsum16(v)); }
; __device__ __forceinline__ unsigned cvt_pk_bf16(float lo, float hi) { unsigned r; asm volatile("v_cvt_pk_bf16_f32 %0, %1, %2" : "=v"(r) : "v"(lo), "v"(hi)); return r; }
; template <int D, int DV, int MODE, int NMAP, int KT> ...
;     ...
;     if (MODE < 2) {
; #pragma unroll
;         for (int mp = 0; mp < NMAP; ++mp) l[mp] = xsum_rows(l[mp]);
;     }
; __global__ void __launch_bounds__(512, 2) mega_fwd(Params P) {
;     ...
;                         const float iv = 1.0f / ll[0]; const size_t row = rb + q0 + wave * 16 + r;
; #pragma unroll
;                         for (int cb = 0; cb < 16; ++cb) { const f32x4 v = o[0][cb] * iv; u32x2 wv; wv.x = cvt_pk_bf16(v[0], v[1]); wv.y = cvt_pk_bf16(v[2], v[3]);
;                             *(u32x2*)(CAT + row * 1024 + h * 256 + cb * 16 + g4 * 4) = wv; }
	v_mfma_f32_16x16x32_bf16 v[2:5], v[98:101], v[66:69], v[2:5]
	v_mov_b32_e32 v66, v106
	s_nop 1
	v_permlane16_swap_b32_e32 v106, v66
	v_add_f32_e32 v66, v106, v66
	v_mov_b32_e32 v67, v66
	s_nop 1
	v_permlane32_swap_b32_e32 v66, v67
	v_add_f32_e32 v66, v66, v67
	v_div_scale_f32 v67, s[6:7], v66, v66, 1.0
	v_rcp_f32_e32 v68, v67
	s_nop 0
	v_fma_f32 v69, -v67, v68, 1.0
	v_fmac_f32_e32 v68, v69, v68
	v_div_scale_f32 v69, vcc, 1.0, v66, 1.0
	v_mul_f32_e32 v70, v69, v68
	v_fma_f32 v71, -v67, v70, v69
	v_fmac_f32_e32 v70, v71, v68
	v_fma_f32 v67, -v67, v70, v69
	v_div_fmas_f32 v67, v67, v68, v70
	v_lshl_add_u64 v[68:69], s[4:5], 0, v[146:147]
	s_lshl_b32 s4, s29, 1
	s_add_u32 s4, s23, s4
	s_addc_u32 s5, s24, 0
	v_lshlrev_b64 v[68:69], 11, v[68:69]
	v_div_fixup_f32 v66, v67, v66, 1.0
	v_lshl_add_u64 v[68:69], s[4:5], 0, v[68:69]
	s_add_i32 s1, s1, s20
	s_add_i32 s27, s27, s28
	v_lshl_add_u64 v[68:69], v[68:69], 0, v[0:1]
	v_pk_mul_f32 v[62:63], v[66:67], v[62:63] op_sel_hi:[0,1]
	v_pk_mul_f32 v[58:59], v[66:67], v[58:59] op_sel_hi:[0,1]
	v_pk_mul_f32 v[54:55], v[66:67], v[54:55] op_sel_hi:[0,1]
	v_pk_mul_f32 v[50:51], v[66:67], v[50:51] op_sel_hi:[0,1]
	v_pk_mul_f32 v[46:47], v[66:67], v[46:47] op_sel_hi:[0,1]
	v_pk_mul_f32 v[42:43], v[66:67], v[42:43] op_sel_hi:[0,1]
	v_pk_mul_f32 v[38:39], v[66:67], v[38:39] op_sel_hi:[0,1]
	v_pk_mul_f32 v[34:35], v[66:67], v[34:35] op_sel_hi:[0,1]
	v_pk_mul_f32 v[30:31], v[66:67], v[30:31] op_sel_hi:[0,1]
	v_pk_mul_f32 v[26:27], v[66:67], v[26:27] op_sel_hi:[0,1]
	v_pk_mul_f32 v[22:23], v[66:67], v[22:23] op_sel_hi:[0,1]
	v_pk_mul_f32 v[18:19], v[66:67], v[18:19] op_sel_hi:[0,1]
	v_pk_mul_f32 v[14:15], v[66:67], v[14:15] op_sel_hi:[0,1]
	v_pk_mul_f32 v[10:11], v[66:67], v[10:11] op_sel_hi:[0,1]
	v_pk_mul_f32 v[6:7], v[66:67], v[6:7] op_sel_hi:[0,1]
	v_pk_mul_f32 v[2:3], v[66:67], v[2:3] op_sel_hi:[0,1]
	s_cmpk_gt_i32 s1, 0x7ff
	v_pk_mul_f32 v[64:65], v[66:67], v[64:65] op_sel_hi:[0,1]
	v_cvt_pk_bf16_f32 v62, v62, v63
	v_cvt_pk_bf16_f32 v63, v64, v65
	global_store_dwordx2 v[68:69], v[62:63], off
	v_pk_mul_f32 v[60:61], v[66:67], v[60:61] op_sel_hi:[0,1]
	v_cvt_pk_bf16_f32 v58, v58, v59
	v_cvt_pk_bf16_f32 v59, v60, v61
	global_store_dwordx2 v[68:69], v[58:59], off offset:32
	v_pk_mul_f32 v[56:57], v[66:67], v[56:57] op_sel_hi:[0,1]
	v_cvt_pk_bf16_f32 v54, v54, v55
	v_cvt_pk_bf16_f32 v55, v56, v57
	global_store_dwordx2 v[68:69], v[54:55], off offset:64
	v_pk_mul_f32 v[52:53], v[66:67], v[52:53] op_sel_hi:[0,1]
	v_cvt_pk_bf16_f32 v50, v50, v51
	v_cvt_pk_bf16_f32 v51, v52, v53
	global_store_dwordx2 v[68:69], v[50:51], off offset:96
	v_pk_mul_f32 v[48:49], v[66:67], v[48:49] op_sel_hi:[0,1]
	v_cvt_pk_bf16_f32 v46, v46, v47
	v_cvt_pk_bf16_f32 v47, v48, v49
	global_store_dwordx2 v[68:69], v[46:47], off offset:128
	v_pk_mul_f32 v[44:45], v[66:67], v[44:45] op_sel_hi:[0,1]
	v_cvt_pk_bf16_f32 v42, v42, v43
	v_cvt_pk_bf16_f32 v43, v44, v45
	global_store_dwordx2 v[68:69], v[42:43], off offset:160
	v_pk_mul_f32 v[40:41], v[66:67], v[40:41] op_sel_hi:[0,1]
	v_cvt_pk_bf16_f32 v38, v38, v39
	v_cvt_pk_bf16_f32 v39, v40, v41
	global_store_dwordx2 v[68:69], v[38:39], off offset:192
	v_pk_mul_f32 v[36:37], v[66:67], v[36:37] op_sel_hi:[0,1]
	v_cvt_pk_bf16_f32 v34, v34, v35
	v_cvt_pk_bf16_f32 v35, v36, v37
	global_store_dwordx2 v[68:69], v[34:35], off offset:224
	v_pk_mul_f32 v[32:33], v[66:67], v[32:33] op_sel_hi:[0,1]
	v_cvt_pk_bf16_f32 v30, v30, v31
	v_cvt_pk_bf16_f32 v31, v32, v33
	global_store_dwordx2 v[68:69], v[30:31], off offset:256
	v_pk_mul_f32 v[28:29], v[66:67], v[28:29] op_sel_hi:[0,1]
	v_cvt_pk_bf16_f32 v26, v26, v27
	v_cvt_pk_bf16_f32 v27, v28, v29
	global_store_dwordx2 v[68:69], v[26:27], off offset:288
	v_pk_mul_f32 v[24:25], v[66:67], v[24:25] op_sel_hi:[0,1]
	v_cvt_pk_bf16_f32 v22, v22, v23
	v_cvt_pk_bf16_f32 v23, v24, v25
	global_store_dwordx2 v[68:69], v[22:23], off offset:320
	v_pk_mul_f32 v[20:21], v[66:67], v[20:21] op_sel_hi:[0,1]
	v_cvt_pk_bf16_f32 v18, v18, v19
	v_cvt_pk_bf16_f32 v19, v20, v21
	global_store_dwordx2 v[68:69], v[18:19], off offset:352
	v_pk_mul_f32 v[16:17], v[66:67], v[16:17] op_sel_hi:[0,1]
	v_cvt_pk_bf16_f32 v14, v14, v15
	v_cvt_pk_bf16_f32 v15, v16, v17
	global_store_dwordx2 v[68:69], v[14:15], off offset:384
	v_pk_mul_f32 v[12:13], v[66:67], v[12:13] op_sel_hi:[0,1]
	v_cvt_pk_bf16_f32 v10, v10, v11
	v_cvt_pk_bf16_f32 v11, v12, v13
	global_store_dwordx2 v[68:69], v[10:11], off offset:416
	v_pk_mul_f32 v[8:9], v[66:67], v[8:9] op_sel_hi:[0,1]
	v_cvt_pk_bf16_f32 v6, v6, v7
	v_cvt_pk_bf16_f32 v7, v8, v9
	global_store_dwordx2 v[68:69], v[6:7], off offset:448
	v_pk_mul_f32 v[4:5], v[66:67], v[4:5] op_sel_hi:[0,1]
	v_cvt_pk_bf16_f32 v2, v2, v3
	v_cvt_pk_bf16_f32 v3, v4, v5
	global_store_dwordx2 v[68:69], v[2:3], off offset:480
	s_cbranch_scc1 .LBB0_608

; template <int D, int DV, int MODE, int NMAP, int KT> ...
;     ...
;     for (int kt = 0; kt < nkt; ++kt) {
;         __syncthreads();
;         const int cur = (kt & 1) * BUF_BYTES;
;         if (kt + 1 < nkt) { AT_STORE(((kt + 1) & 1) * BUF_BYTES); if (kt + 2 < nkt) AT_LOAD(kt + 2); }
;         if (MODE == 0 || kt * KT <= rowmin + 15) {
.LBB0_601:
	v_readfirstlane_b32 s98, v211
	s_nop 3
	s_lshr_b32 s98, s98, 6
	s_cmp_ge_u32 s98, 4
	s_cbranch_scc0 .Lmy_prio_0
	s_setprio 1

; #define LAS __attribute__((address_space(3)))
; template <int D, int DV, int MODE, int NMAP, int KT> ...
;     ...
;         if (MODE == 0 || kt * KT <= rowmin + 15) {
;             const LAS bf16_t* Ks = (const LAS bf16_t*)(lds + cur); const LAS bf16_t* Vt = (const LAS bf16_t*)(lds + cur + KS_BYTES);
;             const bool diag = (MODE != 0) && (kt * KT + KT - 1 > rowmin);
;             bf16x8 pb[NMAP][KK2];
;             f32x4 sall[NMAP][NB];
; #pragma unroll
;             for (int mp = 0; mp < NMAP; ++mp) {
;                 f32x4 (&s)[NB] = sall[mp];
;                 constexpr int KD = D / 32, NBB = (KD >= 8) ? 1 : (8 / KD), NSB = NB / NBB;
;                 bf16x8 kfr[2][NBB][KD];
;     ...
;                 AT_SLOAD(0, 0);
; #pragma unroll
;                 for (int bi = 0; bi < NSB; ++bi) {
;                     if (bi + 1 < NSB) AT_SLOAD(bi + 1, (bi + 1) & 1);
;                     __builtin_amdgcn_sched_barrier(0);
;                     __builtin_amdgcn_s_setprio(1);
; #pragma unroll
;                     for (int x_ = 0; x_ < NBB; ++x_) { const int nb = bi * NBB + x_;
;                         s[nb] = __builtin_amdgcn_mfma_f32_16x16x32_bf16(kfr[bi & 1][x_][0], qf[mp][0], (f32x4){0.f, 0.f, 0.f, 0.f}, 0, 0, 0);
; #pragma unroll
;                         for (int kk = 1; kk < KD; ++kk) s[nb] = __builtin_amdgcn_mfma_f32_16x16x32_bf16(kfr[bi & 1][x_][kk], qf[mp][kk], s[nb], 0, 0, 0); }
;                     __builtin_amdgcn_s_setprio(0);
;                     __builtin_amdgcn_sched_barrier(0);
;                 }
;     ...
;             }
; #pragma unroll
;             for (int mp = 0; mp < NMAP; ++mp) {
;                 f32x4 (&s)[NB] = sall[mp];
;                 if (MODE < 2) {
;                     if (diag) {
; #pragma unroll
;                         for (int nb = 0; nb < NB; ++nb)
; #pragma unroll
;                             for (int j = 0; j < 4; ++j) { if (kt * KT + nb * 16 + g4 * 4 + j > myrow) s[nb][j] = -INFINITY; }
;                     }
;                     float mx = fmaxf(fmaxf(s[0][0], s[0][1]), s[0][2]);
;                     mx = fmaxf(fmaxf(mx, s[0][3]), s[1][0]); mx = fmaxf(fmaxf(mx, s[1][1]), s[1][2]); mx = fmaxf(fmaxf(mx, s[1][3]), s[2][0]);
;                     mx = fmaxf(fmaxf(mx, s[2][1]), s[2][2]); mx = fmaxf(fmaxf(mx, s[2][3]), s[3][0]); mx = fmaxf(fmaxf(mx, s[3][1]), s[3][2]); mx = fmaxf(mx, s[3][3]);
; #pragma unroll
.LBB0_603:
	s_bitcmp1_b32 s15, 0
	s_cselect_b32 s15, 0x11400, 0
	s_add_i32 s15, s15, 0
	v_add3_u32 v184, s15, v148, v170
	ds_read_b128 v[130:133], v184
	ds_read_b128 v[134:137], v184 offset:64
	ds_read_b128 v[138:141], v184 offset:128
	ds_read_b128 v[142:145], v184 offset:192
	ds_read_b128 v[176:179], v184 offset:256
	ds_read_b128 v[180:183], v184 offset:320
	ds_read_b128 v[194:197], v184 offset:384
	ds_read_b128 v[198:201], v184 offset:448
	ds_read_b128 v[202:205], v184 offset:8448
	ds_read_b128 v[206:209], v184 offset:8512
	ds_read_b128 v[226:229], v184 offset:8576
	ds_read_b128 v[230:233], v184 offset:8640
	ds_read_b128 v[234:237], v184 offset:8704
	ds_read_b128 v[238:241], v184 offset:8768
	ds_read_b128 v[242:245], v184 offset:8832
	ds_read_b128 v[246:249], v184 offset:8896
	s_waitcnt lgkmcnt(14)
	v_mfma_f32_16x16x32_bf16 v[130:133], v[130:133], v[66:69], 0
	v_mfma_f32_16x16x32_bf16 v[130:133], v[134:137], v[70:73], v[130:133]
	s_waitcnt lgkmcnt(13)
	v_mfma_f32_16x16x32_bf16 v[130:133], v[138:141], v[74:77], v[130:133]
	s_waitcnt lgkmcnt(12)
	v_mfma_f32_16x16x32_bf16 v[130:133], v[142:145], v[78:81], v[130:133]
	s_waitcnt lgkmcnt(11)
	v_mfma_f32_16x16x32_bf16 v[130:133], v[176:179], v[82:85], v[130:133]
	s_waitcnt lgkmcnt(10)
	v_mfma_f32_16x16x32_bf16 v[130:133], v[180:183], v[86:89], v[130:133]
	s_waitcnt lgkmcnt(9)
	v_mfma_f32_16x16x32_bf16 v[130:133], v[194:197], v[90:93], v[130:133]
	s_waitcnt lgkmcnt(8)
	v_mfma_f32_16x16x32_bf16 v[142:145], v[198:201], v[94:97], v[130:133]
	s_nop 5
	ds_read_b128 v[130:133], v184 offset:16896
	ds_read_b128 v[134:137], v184 offset:16960
	ds_read_b128 v[176:179], v184 offset:17024
	ds_read_b128 v[180:183], v184 offset:17088
	ds_read_b128 v[194:197], v184 offset:17152
	ds_read_b128 v[198:201], v184 offset:17216
	ds_read_b128 v[250:253], v184 offset:17280
	ds_read_b128 v[212:215], v184 offset:17344
	s_waitcnt lgkmcnt(14)
	v_mfma_f32_16x16x32_bf16 v[138:141], v[202:205], v[66:69], 0
	v_mfma_f32_16x16x32_bf16 v[138:141], v[206:209], v[70:73], v[138:141]
	s_waitcnt lgkmcnt(13)
	v_mfma_f32_16x16x32_bf16 v[138:141], v[226:229], v[74:77], v[138:141]
	s_waitcnt lgkmcnt(12)
	v_mfma_f32_16x16x32_bf16 v[138:141], v[230:233], v[78:81], v[138:141]
	s_waitcnt lgkmcnt(11)
	v_mfma_f32_16x16x32_bf16 v[138:141], v[234:237], v[82:85], v[138:141]
	s_waitcnt lgkmcnt(10)
	v_mfma_f32_16x16x32_bf16 v[138:141], v[238:241], v[86:89], v[138:141]
	s_waitcnt lgkmcnt(9)
	v_mfma_f32_16x16x32_bf16 v[138:141], v[242:245], v[90:93], v[138:141]
	s_waitcnt lgkmcnt(8)
	v_mfma_f32_16x16x32_bf16 v[138:141], v[246:249], v[94:97], v[138:141]
	ds_read_b128 v[202:205], v184 offset:25344
	ds_read_b128 v[206:209], v184 offset:25408
	ds_read_b128 v[226:229], v184 offset:25472
	ds_read_b128 v[230:233], v184 offset:25536
	ds_read_b128 v[234:237], v184 offset:25600
	ds_read_b128 v[238:241], v184 offset:25664
	ds_read_b128 v[242:245], v184 offset:25728
	ds_read_b128 v[246:249], v184 offset:25792
	s_waitcnt lgkmcnt(14)
	v_mfma_f32_16x16x32_bf16 v[130:133], v[130:133], v[66:69], 0
	v_mfma_f32_16x16x32_bf16 v[130:133], v[134:137], v[70:73], v[130:133]
	s_waitcnt lgkmcnt(13)
	v_mfma_f32_16x16x32_bf16 v[130:133], v[176:179], v[74:77], v[130:133]
	s_waitcnt lgkmcnt(12)
	v_mfma_f32_16x16x32_bf16 v[130:133], v[180:183], v[78:81], v[130:133]
	s_waitcnt lgkmcnt(11)
	v_mfma_f32_16x16x32_bf16 v[130:133], v[194:197], v[82:85], v[130:133]
	s_waitcnt lgkmcnt(10)
	v_mfma_f32_16x16x32_bf16 v[130:133], v[198:201], v[86:89], v[130:133]
	s_waitcnt lgkmcnt(9)
	v_mfma_f32_16x16x32_bf16 v[130:133], v[250:253], v[90:93], v[130:133]
	s_waitcnt lgkmcnt(8)
	v_mfma_f32_16x16x32_bf16 v[134:137], v[212:215], v[94:97], v[130:133]
	s_waitcnt lgkmcnt(7)
	v_mfma_f32_16x16x32_bf16 v[130:133], v[202:205], v[66:69], 0
	s_waitcnt lgkmcnt(6)
	v_mfma_f32_16x16x32_bf16 v[130:133], v[206:209], v[70:73], v[130:133]
	s_waitcnt lgkmcnt(5)
	v_mfma_f32_16x16x32_bf16 v[130:133], v[226:229], v[74:77], v[130:133]
	s_waitcnt lgkmcnt(4)
	v_mfma_f32_16x16x32_bf16 v[130:133], v[230:233], v[78:81], v[130:133]
	s_waitcnt lgkmcnt(3)
	v_mfma_f32_16x16x32_bf16 v[130:133], v[234:237], v[82:85], v[130:133]
	s_waitcnt lgkmcnt(2)
	v_mfma_f32_16x16x32_bf16 v[130:133], v[238:241], v[86:89], v[130:133]
	s_waitcnt lgkmcnt(1)
	v_mfma_f32_16x16x32_bf16 v[130:133], v[242:245], v[90:93], v[130:133]
	s_waitcnt lgkmcnt(0)
	v_mfma_f32_16x16x32_bf16 v[130:133], v[246:249], v[94:97], v[130:133]
	v_max_f32_e32 v176, v143, v143
	v_max_f32_e32 v177, v142, v142
	v_max_f32_e32 v176, v177, v176
	v_max3_f32 v176, v176, v144, v145
	v_max3_f32 v176, v176, v138, v139
	v_max3_f32 v176, v176, v140, v141
	v_max3_f32 v176, v176, v134, v135
	v_max3_f32 v176, v176, v136, v137
	v_max3_f32 v176, v176, v130, v131
	v_max3_f32 v176, v176, v132, v133
	v_mov_b32_e32 v177, v176
	s_nop 1
	v_permlane16_swap_b32_e32 v176, v177
	v_max_f32_e32 v177, v177, v177
	v_max_f32_e32 v176, v176, v176
	v_max_f32_e32 v176, v176, v177
	v_mov_b32_e32 v177, v176
	s_nop 1
	v_permlane32_swap_b32_e32 v176, v177
	v_max_f32_e32 v177, v177, v177
	v_max_f32_e32 v176, v176, v176
	v_max_f32_e32 v176, v176, v177
	v_mul_f32_e32 v176, 0x3db8aa3b, v176
	v_add_f32_e32 v177, 0x40c00000, v175
	v_cmp_gt_f32_e32 vcc, v176, v177
	s_cbranch_vccz .LBB0_605
; __device__ __forceinline__ unsigned cvt_pk_bf16(float lo, float hi) { unsigned r; asm volatile("v_cvt_pk_bf16_f32 %0, %1, %2" : "=v"(r) : "v"(lo), "v"(hi)); return r; }
; template <int D, int DV, int MODE, int NMAP, int KT> ...
;     ...
;                     if (__any(mx > m[mp] + 6.0f)) {
;                         const float mn = fmaxf(m[mp], mx); const float al = __builtin_amdgcn_exp2f(m[mp] - mn); m[mp] = mn; l[mp] *= al;
; #pragma unroll
;                         for (int cb = 0; cb < DV / 16; ++cb) o[mp][cb] = o[mp][cb] * al;
;                     }
;                     const float nm = -m[mp]; float ps = 0.f;
; #pragma unroll
;                     for (int nb = 0; nb < NB; ++nb)
; #pragma unroll
;                         for (int j = 0; j < 4; ++j) { const float p = __builtin_amdgcn_exp2f(fmaf(s[nb][j], sc, nm)); ps += p; s[nb][j] = p; }
;                     l[mp] += ps;
;                 } else {
;                     const float rowf = __builtin_amdgcn_exp2f(l2g * (float)(myrow - kt * KT));
; #pragma unroll
;                     for (int nb = 0; nb < NB; ++nb)
; #pragma unroll
;                         for (int j = 0; j < 4; ++j) { float p = s[nb][j] * (rowf * ck[nb][j]); if (diag && (kt * KT + nb * 16 + g4 * 4 + j > myrow)) p = 0.f; s[nb][j] = p; }
;                 }
; #pragma unroll
;                 for (int kk = 0; kk < KK2; ++kk) { u32x4 wv; wv.x = cvt_pk_bf16(s[2 * kk][0], s[2 * kk][1]); wv.y = cvt_pk_bf16(s[2 * kk][2], s[2 * kk][3]);
;                     wv.z = cvt_pk_bf16(s[2 * kk + 1][0], s[2 * kk + 1][1]); wv.w = cvt_pk_bf16(s[2 * kk + 1][2], s[2 * kk + 1][3]); pb[mp][kk] = __builtin_bit_cast(bf16x8, wv); }
;             }
;             {
;                 constexpr int CBB = 4, NCB = (DV / 16) / CBB, NVB = KK2 * NCB;
;                 bf16x8 vfr[2][CBB];
;     ...
;                 AT_VLOAD(0, 0);
; #pragma unroll
;                 for (int b_ = 0; b_ < NVB; ++b_) {
;                     if (b_ + 1 < NVB) AT_VLOAD(b_ + 1, (b_ + 1) & 1);
	v_max_f32_e32 v176, v176, v176
	v_max_f32_e32 v177, v175, v175
	v_max_f32_e32 v177, v177, v176
	v_sub_f32_e32 v175, v175, v177
	v_exp_f32_e32 v176, v175
	v_mov_b32_e32 v175, v177
	v_mul_f32_e32 v159, v159, v176
	v_pk_mul_f32 v[64:65], v[64:65], v[176:177] op_sel_hi:[1,0]
	v_pk_mul_f32 v[62:63], v[62:63], v[176:177] op_sel_hi:[1,0]
	v_pk_mul_f32 v[60:61], v[60:61], v[176:177] op_sel_hi:[1,0]
	v_pk_mul_f32 v[58:59], v[58:59], v[176:177] op_sel_hi:[1,0]
	v_pk_mul_f32 v[56:57], v[56:57], v[176:177] op_sel_hi:[1,0]
	v_pk_mul_f32 v[54:55], v[54:55], v[176:177] op_sel_hi:[1,0]
	v_pk_mul_f32 v[52:53], v[52:53], v[176:177] op_sel_hi:[1,0]
	v_pk_mul_f32 v[50:51], v[50:51], v[176:177] op_sel_hi:[1,0]
	v_pk_mul_f32 v[48:49], v[48:49], v[176:177] op_sel_hi:[1,0]
	v_pk_mul_f32 v[46:47], v[46:47], v[176:177] op_sel_hi:[1,0]
	v_pk_mul_f32 v[44:45], v[44:45], v[176:177] op_sel_hi:[1,0]
	v_pk_mul_f32 v[42:43], v[42:43], v[176:177] op_sel_hi:[1,0]
	v_pk_mul_f32 v[40:41], v[40:41], v[176:177] op_sel_hi:[1,0]
	v_pk_mul_f32 v[38:39], v[38:39], v[176:177] op_sel_hi:[1,0]
	v_pk_mul_f32 v[36:37], v[36:37], v[176:177] op_sel_hi:[1,0]
	v_pk_mul_f32 v[34:35], v[34:35], v[176:177] op_sel_hi:[1,0]
	v_pk_mul_f32 v[32:33], v[32:33], v[176:177] op_sel_hi:[1,0]
	v_pk_mul_f32 v[30:31], v[30:31], v[176:177] op_sel_hi:[1,0]
	v_pk_mul_f32 v[28:29], v[28:29], v[176:177] op_sel_hi:[1,0]
	v_pk_mul_f32 v[26:27], v[26:27], v[176:177] op_sel_hi:[1,0]
	v_pk_mul_f32 v[24:25], v[24:25], v[176:177] op_sel_hi:[1,0]
	v_pk_mul_f32 v[22:23], v[22:23], v[176:177] op_sel_hi:[1,0]
	v_pk_mul_f32 v[20:21], v[20:21], v[176:177] op_sel_hi:[1,0]
	v_pk_mul_f32 v[18:19], v[18:19], v[176:177] op_sel_hi:[1,0]
	v_pk_mul_f32 v[16:17], v[16:17], v[176:177] op_sel_hi:[1,0]
	v_pk_mul_f32 v[14:15], v[14:15], v[176:177] op_sel_hi:[1,0]
	v_pk_mul_f32 v[12:13], v[12:13], v[176:177] op_sel_hi:[1,0]
	v_pk_mul_f32 v[10:11], v[10:11], v[176:177] op_sel_hi:[1,0]
	v_pk_mul_f32 v[8:9], v[8:9], v[176:177] op_sel_hi:[1,0]
	v_pk_mul_f32 v[6:7], v[6:7], v[176:177] op_sel_hi:[1,0]
	v_pk_mul_f32 v[4:5], v[4:5], v[176:177] op_sel_hi:[1,0]
	v_pk_mul_f32 v[2:3], v[2:3], v[176:177] op_sel_hi:[1,0]
.LBB0_605:
	v_fma_f32 v142, v142, s0, -v175
	v_exp_f32_e32 v142, v142
	v_fma_f32 v143, v143, s0, -v175
	v_exp_f32_e32 v143, v143
	v_fma_f32 v144, v144, s0, -v175
	v_exp_f32_e32 v144, v144
	v_fma_f32 v145, v145, s0, -v175
	v_exp_f32_e32 v145, v145
	v_fma_f32 v138, v138, s0, -v175
	v_add_f32_e32 v176, 0, v142
	v_exp_f32_e32 v138, v138
	v_fma_f32 v139, v139, s0, -v175
	v_add_f32_e32 v176, v143, v176
	v_exp_f32_e32 v139, v139
	v_fma_f32 v140, v140, s0, -v175
	v_add_f32_e32 v176, v144, v176
	v_exp_f32_e32 v140, v140
	v_fma_f32 v141, v141, s0, -v175
	v_add_f32_e32 v176, v145, v176
	v_exp_f32_e32 v141, v141
	v_fma_f32 v134, v134, s0, -v175
	v_add_f32_e32 v176, v138, v176
	v_exp_f32_e32 v177, v134
	v_add_f32_e32 v176, v139, v176
	v_add_f32_e32 v176, v140, v176
	v_add_f32_e32 v176, v141, v176
	v_fma_f32 v135, v135, s0, -v175
	v_add_f32_e32 v134, v177, v176
	v_exp_f32_e32 v176, v135
	v_fma_f32 v135, v136, s0, -v175
	v_exp_f32_e32 v178, v135
	v_fma_f32 v135, v137, s0, -v175
	v_exp_f32_e32 v179, v135
	v_fma_f32 v130, v130, s0, -v175
	v_exp_f32_e32 v180, v130
	v_fma_f32 v131, v131, s0, -v175
	v_add_f32_e32 v134, v176, v134
	v_exp_f32_e32 v181, v131
	v_fma_f32 v131, v132, s0, -v175
	v_add_f32_e32 v134, v178, v134
	v_exp_f32_e32 v182, v131
	v_fma_f32 v131, v133, s0, -v175
	v_add_f32_e32 v134, v179, v134
	v_exp_f32_e32 v133, v131
	v_add_f32_e32 v130, v180, v134
	v_add_f32_e32 v130, v181, v130
	v_add_f32_e32 v130, v182, v130
	v_add3_u32 v184, s15, v158, v149
	v_add_f32_e32 v130, v133, v130
	v_add_u32_e32 v210, 0x8000, v184
	v_add_u32_e32 v212, 0x8800, v184
	v_add_u32_e32 v213, 0x9000, v184
	v_add_u32_e32 v214, 0x9800, v184
	v_add_u32_e32 v215, 0xa800, v184
	v_add_u32_e32 v216, 0xb000, v184
	v_add_u32_e32 v217, 0xb800, v184
	v_add_u32_e32 v226, 0xc000, v184
	v_add_f32_e32 v159, v159, v130
	v_cvt_pk_bf16_f32 v134, v142, v143
	v_cvt_pk_bf16_f32 v135, v144, v145
	v_cvt_pk_bf16_f32 v136, v138, v139
	v_cvt_pk_bf16_f32 v137, v140, v141
	v_cvt_pk_bf16_f32 v130, v177, v176
	v_cvt_pk_bf16_f32 v131, v178, v179
	v_cvt_pk_bf16_f32 v132, v180, v181
	v_cvt_pk_bf16_f32 v133, v182, v133
	ds_read_b64 v[138:139], v210 offset:1024
	ds_read_b64 v[140:141], v210 offset:1056
	ds_read_b64 v[142:143], v212 offset:1280
	ds_read_b64 v[144:145], v212 offset:1312
	ds_read_b64 v[176:177], v213 offset:1536
	ds_read_b64 v[178:179], v213 offset:1568
	ds_read_b64 v[180:181], v214 offset:1792
	ds_read_b64 v[182:183], v214 offset:1824
	ds_read_b64 v[194:195], v215
	ds_read_b64 v[196:197], v215 offset:32
	ds_read_b64 v[198:199], v216 offset:256
	ds_read_b64 v[200:201], v216 offset:288
	ds_read_b64 v[202:203], v217 offset:512
	ds_read_b64 v[204:205], v217 offset:544
	ds_read_b64 v[206:207], v226 offset:768
	ds_read_b64 v[208:209], v226 offset:800
	v_add_u32_e32 v185, 0x8400, v184
	s_waitcnt lgkmcnt(14)
	v_mfma_f32_16x16x32_bf16 v[62:65], v[138:141], v[134:137], v[62:65]
	s_waitcnt lgkmcnt(12)
	v_mfma_f32_16x16x32_bf16 v[58:61], v[142:145], v[134:137], v[58:61]
	s_waitcnt lgkmcnt(10)
	v_mfma_f32_16x16x32_bf16 v[54:57], v[176:179], v[134:137], v[54:57]
	s_waitcnt lgkmcnt(8)
; template <int D, int DV, int MODE, int NMAP, int KT> ...
;     ...
;                 for (int b_ = 0; b_ < NVB; ++b_) {
;                     if (b_ + 1 < NVB) AT_VLOAD(b_ + 1, (b_ + 1) & 1);
;                     __builtin_amdgcn_sched_barrier(0);
;                     const int kk_ = b_ / NCB, c0_ = (b_ % NCB) * CBB;
;                     __builtin_amdgcn_s_setprio(1);
; #pragma unroll
;                     for (int x_ = 0; x_ < CBB; ++x_)
; #pragma unroll
;                         for (int mp = 0; mp < NMAP; ++mp) o[mp][c0_ + x_] = __builtin_amdgcn_mfma_f32_16x16x32_bf16(vfr[b_ & 1][x_], pb[mp][kk_], o[mp][c0_ + x_], 0, 0, 0);
;                     __builtin_amdgcn_s_setprio(0);
;                     __builtin_amdgcn_sched_barrier(0);
;                 }
	v_mfma_f32_16x16x32_bf16 v[50:53], v[180:183], v[134:137], v[50:53]
	v_add_u32_e32 v227, 0xc800, v184
	v_add_u32_e32 v228, 0xd000, v184
	v_add_u32_e32 v229, 0xd800, v184
	v_add_u32_e32 v230, 0xe000, v184
	ds_read_b64 v[138:139], v227 offset:1024
	ds_read_b64 v[140:141], v227 offset:1056
	ds_read_b64 v[142:143], v228 offset:1280
	ds_read_b64 v[144:145], v228 offset:1312
	ds_read_b64 v[176:177], v229 offset:1536
	ds_read_b64 v[178:179], v229 offset:1568
	ds_read_b64 v[180:181], v230 offset:1792
	ds_read_b64 v[182:183], v230 offset:1824
	s_waitcnt lgkmcnt(14)
	v_mfma_f32_16x16x32_bf16 v[46:49], v[194:197], v[134:137], v[46:49]
	s_waitcnt lgkmcnt(12)
	v_mfma_f32_16x16x32_bf16 v[42:45], v[198:201], v[134:137], v[42:45]
	s_waitcnt lgkmcnt(10)
	v_mfma_f32_16x16x32_bf16 v[38:41], v[202:205], v[134:137], v[38:41]
	s_waitcnt lgkmcnt(8)
	v_mfma_f32_16x16x32_bf16 v[34:37], v[206:209], v[134:137], v[34:37]
	v_add_u32_e32 v231, 0xf000, v184
	v_add_u32_e32 v232, 0xf800, v184
	v_add_u32_e32 v202, 0x7800, v185
	v_add_u32_e32 v185, 0x8000, v185
	ds_read_b64 v[194:195], v231
	ds_read_b64 v[196:197], v231 offset:32
	ds_read_b64 v[198:199], v232 offset:256
	ds_read_b64 v[200:201], v232 offset:288
	ds_read_b64 v[204:205], v202 offset:1568
	ds_read_b64 v[202:203], v202 offset:1536
	ds_read_b64 v[206:207], v185 offset:1792
	ds_read_b64 v[208:209], v185 offset:1824
	s_waitcnt lgkmcnt(14)
	v_mfma_f32_16x16x32_bf16 v[30:33], v[138:141], v[134:137], v[30:33]
	s_waitcnt lgkmcnt(12)
	v_mfma_f32_16x16x32_bf16 v[26:29], v[142:145], v[134:137], v[26:29]
	s_waitcnt lgkmcnt(10)
	v_mfma_f32_16x16x32_bf16 v[22:25], v[176:179], v[134:137], v[22:25]
	s_waitcnt lgkmcnt(8)
	v_mfma_f32_16x16x32_bf16 v[18:21], v[180:183], v[134:137], v[18:21]
	ds_read_b64 v[138:139], v210 offset:1088
	ds_read_b64 v[140:141], v210 offset:1120
	ds_read_b64 v[142:143], v212 offset:1344
	ds_read_b64 v[144:145], v212 offset:1376
	ds_read_b64 v[176:177], v213 offset:1600
	ds_read_b64 v[178:179], v213 offset:1632
	ds_read_b64 v[180:181], v214 offset:1856
	ds_read_b64 v[182:183], v214 offset:1888
	v_add_u32_e32 v184, 0x8440, v184
	s_waitcnt lgkmcnt(14)
	v_mfma_f32_16x16x32_bf16 v[14:17], v[194:197], v[134:137], v[14:17]
	s_waitcnt lgkmcnt(12)
	v_mfma_f32_16x16x32_bf16 v[10:13], v[198:201], v[134:137], v[10:13]
	s_waitcnt lgkmcnt(10)
	v_mfma_f32_16x16x32_bf16 v[6:9], v[202:205], v[134:137], v[6:9]
	s_waitcnt lgkmcnt(8)
	v_mfma_f32_16x16x32_bf16 v[2:5], v[206:209], v[134:137], v[2:5]
	ds_read_b64 v[134:135], v215 offset:64
	ds_read_b64 v[136:137], v215 offset:96
	ds_read_b64 v[194:195], v216 offset:320
	ds_read_b64 v[196:197], v216 offset:352
	ds_read_b64 v[198:199], v217 offset:576
	ds_read_b64 v[200:201], v217 offset:608
	ds_read_b64 v[202:203], v226 offset:832
	ds_read_b64 v[204:205], v226 offset:864
	s_waitcnt lgkmcnt(14)
	v_mfma_f32_16x16x32_bf16 v[62:65], v[138:141], v[130:133], v[62:65]
	s_waitcnt lgkmcnt(12)
	v_mfma_f32_16x16x32_bf16 v[58:61], v[142:145], v[130:133], v[58:61]
	s_waitcnt lgkmcnt(10)
	v_mfma_f32_16x16x32_bf16 v[54:57], v[176:179], v[130:133], v[54:57]
	s_waitcnt lgkmcnt(8)
	v_mfma_f32_16x16x32_bf16 v[50:53], v[180:183], v[130:133], v[50:53]
	ds_read_b64 v[138:139], v227 offset:1088
	ds_read_b64 v[140:141], v227 offset:1120
	ds_read_b64 v[142:143], v228 offset:1344
	ds_read_b64 v[144:145], v228 offset:1376
	ds_read_b64 v[176:177], v229 offset:1600
	ds_read_b64 v[178:179], v229 offset:1632
	ds_read_b64 v[180:181], v230 offset:1856
	ds_read_b64 v[182:183], v230 offset:1888
	s_waitcnt lgkmcnt(14)
	v_mfma_f32_16x16x32_bf16 v[46:49], v[134:137], v[130:133], v[46:49]
	s_waitcnt lgkmcnt(12)
	v_mfma_f32_16x16x32_bf16 v[42:45], v[194:197], v[130:133], v[42:45]
	s_waitcnt lgkmcnt(10)
	v_mfma_f32_16x16x32_bf16 v[38:41], v[198:201], v[130:133], v[38:41]
	s_waitcnt lgkmcnt(8)
	v_mfma_f32_16x16x32_bf16 v[34:37], v[202:205], v[130:133], v[34:37]
	ds_read_b64 v[134:135], v231 offset:64
	ds_read_b64 v[136:137], v231 offset:96
	ds_read_b64 v[194:195], v232 offset:320
	ds_read_b64 v[196:197], v232 offset:352
	v_add_u32_e32 v185, 0x7800, v184
	v_add_u32_e32 v184, 0x8000, v184
	ds_read_b64 v[198:199], v185 offset:1536
	ds_read_b64 v[200:201], v185 offset:1568
	ds_read_b64 v[202:203], v184 offset:1792
	ds_read_b64 v[204:205], v184 offset:1824
	s_waitcnt lgkmcnt(14)
	v_mfma_f32_16x16x32_bf16 v[30:33], v[138:141], v[130:133], v[30:33]
	s_waitcnt lgkmcnt(12)
	v_mfma_f32_16x16x32_bf16 v[26:29], v[142:145], v[130:133], v[26:29]
	s_waitcnt lgkmcnt(10)
	v_mfma_f32_16x16x32_bf16 v[22:25], v[176:179], v[130:133], v[22:25]
	s_waitcnt lgkmcnt(8)
	v_mfma_f32_16x16x32_bf16 v[18:21], v[180:183], v[130:133], v[18:21]
	s_waitcnt lgkmcnt(6)
	v_mfma_f32_16x16x32_bf16 v[14:17], v[134:137], v[130:133], v[14:17]
	s_waitcnt lgkmcnt(4)
	v_mfma_f32_16x16x32_bf16 v[10:13], v[194:197], v[130:133], v[10:13]
	s_waitcnt lgkmcnt(2)
	v_mfma_f32_16x16x32_bf16 v[6:9], v[198:201], v[130:133], v[6:9]
	s_waitcnt lgkmcnt(0)
	v_mfma_f32_16x16x32_bf16 v[2:5], v[202:205], v[130:133], v[2:5]
	s_add_i32 s44, s44, 64
	v_lshl_add_u64 v[150:151], v[150:151], 0, s[72:73]
	v_lshl_add_u64 v[152:153], v[152:153], 0, s[72:73]
	v_lshl_add_u64 v[154:155], v[154:155], 0, s[72:73]
	s_cmpk_lg_i32 s44, 0xc0
	v_lshl_add_u64 v[156:157], v[156:157], 0, s[72:73]
	s_cbranch_scc0 .LBB0_597
	s_mov_b32 s15, s14
	s_branch .LBB0_601

; __device__ __forceinline__ unsigned xb_add(unsigned* p, unsigned v) { return __hip_atomic_fetch_add(p, v, __ATOMIC_RELAXED, __HIP_MEMORY_SCOPE_AGENT); }
; #define GRID_BAR() do { XcdBarrier b_; b_.bar = (unsigned*)P.ws; b_.x = xb_xcc_id(); b_.st = (volatile LAS unsigned*)(lds + 156144); xcd_barrier_fast(b_); } while (0)
; __device__ __forceinline__ void xcd_barrier_fast(const XcdBarrier& b) {
;     asm volatile("s_waitcnt vmcnt(0)" ::: "memory");
;     __syncthreads();
;     if (threadIdx.x == 0) {
;         unsigned* bar = b.bar;
;         __builtin_amdgcn_s_waitcnt(0);
;         unsigned nloc = b.st[0], nx = b.st[1];
;         const unsigned old = xb_add(&bar[XB_XSUB(b.x)], 1u);
; __global__ void __launch_bounds__(512, 2) mega_fwd(Params P) {
;     ...
;                 __syncthreads();
;                 GRID_BAR();
.LBB0_608:
	s_setprio 0
	s_waitcnt lgkmcnt(0)
	s_barrier
	s_getreg_b32 s1, hwreg(HW_REG_XCC_ID, 0, 4)
	s_waitcnt vmcnt(0)
	s_barrier
	s_and_saveexec_b64 s[2:3], s[84:85]
	s_cbranch_execz .LBB0_645
	v_readlane_b32 s4, v255, 10
	s_waitcnt vmcnt(0) expcnt(0) lgkmcnt(0)
	s_mov_b64 s[6:7], exec
	v_mov_b32_e32 v0, s4
	v_readlane_b32 s4, v255, 11
	ds_read_b32 v3, v0
	s_lshl_b32 s1, s1, 8
	v_mov_b32_e32 v0, s4
	ds_read_b32 v2, v0
	v_readlane_b32 s8, v254, 3
	s_and_b32 s1, s1, 0xf00
	v_readlane_b32 s10, v254, 5
	v_mbcnt_lo_u32_b32 v0, s6, 0
	v_readlane_b32 s11, v254, 6
	s_add_u32 s4, s10, s1
	v_mbcnt_hi_u32_b32 v0, s7, v0
	v_readlane_b32 s9, v254, 4
	s_addc_u32 s5, s11, 0
	v_cmp_eq_u32_e32 vcc, 0, v0
	s_and_saveexec_b64 s[8:9], vcc
	s_cbranch_execz .LBB0_611
	s_bcnt1_i32_b64 s1, s[6:7]
	v_mov_b32_e32 v4, s1
	v_mov_b32_e32 v5, 0x1000
	global_atomic_add v4, v5, v4, s[4:5] offset:1024 sc0

; template <int D, int DV, int MODE, int NMAP, int KT> ...
;     ...
;             for (int mp = 0; mp < NMAP; ++mp) {
;                 f32x4 (&s)[NB] = sall[mp];
;                 constexpr int KD = D / 32, NBB = (KD >= 8) ? 1 : (8 / KD), NSB = NB / NBB;
;                 bf16x8 kfr[2][NBB][KD];
;     ...
;                 AT_SLOAD(0, 0);
; #pragma unroll
;                 for (int bi = 0; bi < NSB; ++bi) {
;                     if (bi + 1 < NSB) AT_SLOAD(bi + 1, (bi + 1) & 1);
;                     __builtin_amdgcn_sched_barrier(0);
;                     __builtin_amdgcn_s_setprio(1);
; #pragma unroll
;                     for (int x_ = 0; x_ < NBB; ++x_) { const int nb = bi * NBB + x_;
;                         s[nb] = __builtin_amdgcn_mfma_f32_16x16x32_bf16(kfr[bi & 1][x_][0], qf[mp][0], (f32x4){0.f, 0.f, 0.f, 0.f}, 0, 0, 0);
; #pragma unroll
;                         for (int kk = 1; kk < KD; ++kk) s[nb] = __builtin_amdgcn_mfma_f32_16x16x32_bf16(kfr[bi & 1][x_][kk], qf[mp][kk], s[nb], 0, 0, 0); }
;                     __builtin_amdgcn_s_setprio(0);
;                     __builtin_amdgcn_sched_barrier(0);
;                 }
;     ...
;             }
; #pragma unroll
;             for (int mp = 0; mp < NMAP; ++mp) {
;                 f32x4 (&s)[NB] = sall[mp];
;                 if (MODE < 2) {
;                     if (diag) {
; #pragma unroll
;                         for (int nb = 0; nb < NB; ++nb)
; #pragma unroll
;                             for (int j = 0; j < 4; ++j) { if (kt * KT + nb * 16 + g4 * 4 + j > myrow) s[nb][j] = -INFINITY; }
;                     }
;                     float mx = fmaxf(fmaxf(s[0][0], s[0][1]), s[0][2]);
;                     mx = fmaxf(fmaxf(mx, s[0][3]), s[1][0]); mx = fmaxf(fmaxf(mx, s[1][1]), s[1][2]); mx = fmaxf(fmaxf(mx, s[1][3]), s[2][0]);
;                     mx = fmaxf(fmaxf(mx, s[2][1]), s[2][2]); mx = fmaxf(fmaxf(mx, s[2][3]), s[3][0]); mx = fmaxf(fmaxf(mx, s[3][1]), s[3][2]); mx = fmaxf(mx, s[3][3]);
; #pragma unroll
;                     for (int nb = 4; nb < NB; ++nb) { mx = fmaxf(fmaxf(mx, s[nb][0]), s[nb][1]); mx = fmaxf(fmaxf(mx, s[nb][2]), s[nb][3]); }
;                     mx = xmax_rows(mx) * sc;
;                     if (__any(mx > m[mp] + 6.0f)) {
;                         const float mn = fmaxf(m[mp], mx); const float al = __builtin_amdgcn_exp2f(m[mp] - mn); m[mp] = mn; l[mp] *= al;
; #pragma unroll
.LBB0_795:
	s_cmp_gt_i32 s19, s33
	s_cbranch_scc1 .LBB0_797
	s_bitcmp1_b32 s16, 0
	s_cselect_b32 s16, 0xd000, 0
	s_add_i32 s40, s16, 0
	v_lshlrev_b32_e32 v135, 1, v87
	v_add_u32_e32 v184, s40, v135
	v_add_u32_e32 v156, v184, v123
	ds_read_b128 v[66:69], v156
	ds_read_b128 v[70:73], v156 offset:64
	ds_read_b128 v[136:139], v156 offset:2304
	ds_read_b128 v[140:143], v156 offset:2368
	ds_read_b128 v[144:147], v156 offset:4608
	ds_read_b128 v[148:151], v156 offset:4672
	ds_read_b128 v[152:155], v156 offset:6912
	ds_read_b128 v[156:159], v156 offset:6976
	v_add3_u32 v135, s40, v123, v135
	ds_read_b128 v[160:163], v135 offset:9216
	ds_read_b128 v[164:167], v135 offset:9280
	v_add_u32_e32 v135, v184, v124
	ds_read_b128 v[168:171], v135 offset:9216
	ds_read_b128 v[172:175], v135 offset:9280
	v_add_u32_e32 v135, v184, v125
	ds_read_b128 v[176:179], v135 offset:9216
	ds_read_b128 v[180:183], v135 offset:9280
	v_add_u32_e32 v135, v184, v126
	ds_read_b128 v[194:197], v135 offset:9216
	ds_read_b128 v[198:201], v135 offset:9280
	s_add_i32 s16, s19, 0x7f
	s_waitcnt lgkmcnt(14)
	v_mfma_f32_16x16x32_bf16 v[66:69], v[66:69], v[34:37], 0
	v_mfma_f32_16x16x32_bf16 v[66:69], v[70:73], v[38:41], v[66:69]
	s_waitcnt lgkmcnt(13)
	v_mfma_f32_16x16x32_bf16 v[70:73], v[136:139], v[34:37], 0
	s_waitcnt lgkmcnt(12)
	v_mfma_f32_16x16x32_bf16 v[70:73], v[140:143], v[38:41], v[70:73]
	s_waitcnt lgkmcnt(11)
	v_mfma_f32_16x16x32_bf16 v[136:139], v[144:147], v[34:37], 0
	s_waitcnt lgkmcnt(9)
	v_mfma_f32_16x16x32_bf16 v[140:143], v[152:155], v[34:37], 0
	v_mfma_f32_16x16x32_bf16 v[136:139], v[148:151], v[38:41], v[136:139]
	s_waitcnt lgkmcnt(8)
	v_mfma_f32_16x16x32_bf16 v[140:143], v[156:159], v[38:41], v[140:143]
	s_waitcnt lgkmcnt(7)
	v_mfma_f32_16x16x32_bf16 v[144:147], v[160:163], v[34:37], 0
	s_waitcnt lgkmcnt(5)
	v_mfma_f32_16x16x32_bf16 v[148:151], v[168:171], v[34:37], 0
	s_waitcnt lgkmcnt(3)
	v_mfma_f32_16x16x32_bf16 v[152:155], v[176:179], v[34:37], 0
	s_waitcnt lgkmcnt(1)
	v_mfma_f32_16x16x32_bf16 v[156:159], v[194:197], v[34:37], 0
	v_mfma_f32_16x16x32_bf16 v[144:147], v[164:167], v[38:41], v[144:147]
	v_mfma_f32_16x16x32_bf16 v[148:151], v[172:175], v[38:41], v[148:151]
	v_mfma_f32_16x16x32_bf16 v[152:155], v[180:183], v[38:41], v[152:155]
	s_waitcnt lgkmcnt(0)
	v_mfma_f32_16x16x32_bf16 v[156:159], v[198:201], v[38:41], v[156:159]
	v_cvt_f32_i32_e32 v135, v134
	s_cmp_gt_i32 s16, s31
	v_add_u32_e32 v160, s19, v89
	s_cselect_b64 s[16:17], -1, 0
	v_mul_f32_e32 v135, v88, v135
	v_exp_f32_e32 v135, v135
	v_cmp_gt_i32_e32 vcc, v160, v122
	s_and_b64 s[42:43], s[16:17], vcc
	v_cmp_ge_i32_e32 vcc, v160, v122
	v_mul_f32_e32 v161, v90, v135
	v_mul_f32_e32 v66, v161, v66
	v_mul_f32_e32 v161, v92, v135
	v_mul_f32_e32 v68, v161, v68
	v_add_u32_e32 v161, 2, v160
	v_mul_f32_e32 v162, v91, v135
	v_cndmask_b32_e64 v66, v66, 0, s[42:43]
	s_and_b64 s[42:43], s[16:17], vcc
	v_cmp_gt_i32_e32 vcc, v161, v122
	v_mul_f32_e32 v161, v93, v135
	v_mul_f32_e32 v67, v162, v67
	v_mul_f32_e32 v69, v161, v69
	v_add_u32_e32 v161, 3, v160
	v_cndmask_b32_e64 v67, v67, 0, s[42:43]
	s_and_b64 s[42:43], s[16:17], vcc
	v_cmp_gt_i32_e32 vcc, v161, v122
	v_add_u32_e32 v161, 16, v160
	v_cndmask_b32_e64 v68, v68, 0, s[42:43]
	s_and_b64 s[42:43], s[16:17], vcc
	v_cmp_gt_i32_e32 vcc, v161, v122
	v_mul_f32_e32 v161, v95, v135
	v_mul_f32_e32 v71, v161, v71
	v_add_u32_e32 v161, 17, v160
	v_cndmask_b32_e64 v69, v69, 0, s[42:43]
	v_mul_f32_e32 v162, v94, v135
	s_and_b64 s[42:43], s[16:17], vcc
	v_cmp_gt_i32_e32 vcc, v161, v122
	v_mul_f32_e32 v161, v96, v135
	v_mul_f32_e32 v70, v162, v70
	v_mul_f32_e32 v72, v161, v72
	v_add_u32_e32 v161, 18, v160
	v_cndmask_b32_e64 v70, v70, 0, s[42:43]
	s_and_b64 s[42:43], s[16:17], vcc
	v_cmp_gt_i32_e32 vcc, v161, v122
	v_mul_f32_e32 v161, v97, v135
	v_mul_f32_e32 v73, v161, v73
	v_add_u32_e32 v161, 19, v160
	v_cndmask_b32_e64 v71, v71, 0, s[42:43]
	s_and_b64 s[42:43], s[16:17], vcc
	v_cmp_gt_i32_e32 vcc, v161, v122
	v_add_u32_e32 v161, 32, v160
	v_cndmask_b32_e64 v72, v72, 0, s[42:43]
	s_and_b64 s[42:43], s[16:17], vcc
	v_mul_f32_e32 v162, v98, v135
	v_cmp_gt_i32_e32 vcc, v161, v122
	v_cndmask_b32_e64 v73, v73, 0, s[42:43]
	v_mul_f32_e32 v136, v162, v136
	s_and_b64 s[42:43], s[16:17], vcc
	v_cndmask_b32_e64 v161, v136, 0, s[42:43]
	v_mul_f32_e32 v136, v99, v135
	v_mul_f32_e32 v136, v136, v137
	v_add_u32_e32 v137, 33, v160
	v_cmp_gt_i32_e32 vcc, v137, v122
	s_and_b64 s[42:43], s[16:17], vcc
	v_add_u32_e32 v137, 34, v160
	v_cndmask_b32_e64 v162, v136, 0, s[42:43]
	v_mul_f32_e32 v136, v100, v135
	v_cmp_gt_i32_e32 vcc, v137, v122
	v_mul_f32_e32 v136, v136, v138
	s_and_b64 s[42:43], s[16:17], vcc
	v_add_u32_e32 v137, 35, v160
	v_cndmask_b32_e64 v163, v136, 0, s[42:43]
	v_mul_f32_e32 v136, v101, v135
	v_cmp_gt_i32_e32 vcc, v137, v122
	v_mul_f32_e32 v136, v136, v139
	s_and_b64 s[42:43], s[16:17], vcc
	v_cndmask_b32_e64 v164, v136, 0, s[42:43]
	v_add_u32_e32 v136, 48, v160
	v_mul_f32_e32 v137, v102, v135
	v_cmp_gt_i32_e32 vcc, v136, v122
	v_mul_f32_e32 v137, v137, v140
	s_and_b64 s[42:43], s[16:17], vcc
	v_cndmask_b32_e64 v165, v137, 0, s[42:43]
	v_add_u32_e32 v137, 49, v160
	v_mul_f32_e32 v136, v103, v135
	v_cmp_gt_i32_e32 vcc, v137, v122
	v_mul_f32_e32 v136, v136, v141
	s_and_b64 s[42:43], s[16:17], vcc
	v_add_u32_e32 v137, 50, v160
	v_cndmask_b32_e64 v166, v136, 0, s[42:43]
	v_mul_f32_e32 v136, v104, v135
	v_cmp_gt_i32_e32 vcc, v137, v122
	v_mul_f32_e32 v136, v136, v142
	s_and_b64 s[42:43], s[16:17], vcc
	v_add_u32_e32 v137, 51, v160
	v_cndmask_b32_e64 v167, v136, 0, s[42:43]
	v_mul_f32_e32 v136, v105, v135
	v_cmp_gt_i32_e32 vcc, v137, v122
	v_mul_f32_e32 v136, v136, v143
; __device__ __forceinline__ unsigned cvt_pk_bf16(float lo, float hi) { unsigned r; asm volatile("v_cvt_pk_bf16_f32 %0, %1, %2" : "=v"(r) : "v"(lo), "v"(hi)); return r; }
; template <int D, int DV, int MODE, int NMAP, int KT> ...
;     ...
;                     const float rowf = __builtin_amdgcn_exp2f(l2g * (float)(myrow - kt * KT));
; #pragma unroll
;                     for (int nb = 0; nb < NB; ++nb)
; #pragma unroll
;                         for (int j = 0; j < 4; ++j) { float p = s[nb][j] * (rowf * ck[nb][j]); if (diag && (kt * KT + nb * 16 + g4 * 4 + j > myrow)) p = 0.f; s[nb][j] = p; }
;                 }
; #pragma unroll
;                 for (int kk = 0; kk < KK2; ++kk) { u32x4 wv; wv.x = cvt_pk_bf16(s[2 * kk][0], s[2 * kk][1]); wv.y = cvt_pk_bf16(s[2 * kk][2], s[2 * kk][3]);
;                     wv.z = cvt_pk_bf16(s[2 * kk + 1][0], s[2 * kk + 1][1]); wv.w = cvt_pk_bf16(s[2 * kk + 1][2], s[2 * kk + 1][3]); pb[mp][kk] = __builtin_bit_cast(bf16x8, wv); }
;             }
;             {
;                 constexpr int CBB = 4, NCB = (DV / 16) / CBB, NVB = KK2 * NCB;
;                 bf16x8 vfr[2][CBB];
;     ...
;                 AT_VLOAD(0, 0);
; #pragma unroll
;                 for (int b_ = 0; b_ < NVB; ++b_) {
;                     if (b_ + 1 < NVB) AT_VLOAD(b_ + 1, (b_ + 1) & 1);
	s_and_b64 s[42:43], s[16:17], vcc
	v_cndmask_b32_e64 v143, v136, 0, s[42:43]
	v_add_u32_e32 v136, 64, v160
	v_mul_f32_e32 v137, v106, v135
	v_cmp_gt_i32_e32 vcc, v136, v122
	v_mul_f32_e32 v137, v137, v144
	s_and_b64 s[42:43], s[16:17], vcc
	v_cndmask_b32_e64 v144, v137, 0, s[42:43]
	v_add_u32_e32 v137, 0x41, v160
	v_mul_f32_e32 v136, v107, v135
	v_cmp_gt_i32_e32 vcc, v137, v122
	v_mul_f32_e32 v136, v136, v145
	s_and_b64 s[42:43], s[16:17], vcc
	v_add_u32_e32 v137, 0x42, v160
	v_cndmask_b32_e64 v145, v136, 0, s[42:43]
	v_mul_f32_e32 v136, v108, v135
	v_cmp_gt_i32_e32 vcc, v137, v122
	v_mul_f32_e32 v136, v136, v146
	s_and_b64 s[42:43], s[16:17], vcc
	v_add_u32_e32 v137, 0x43, v160
	v_cndmask_b32_e64 v146, v136, 0, s[42:43]
	v_mul_f32_e32 v136, v109, v135
	v_cmp_gt_i32_e32 vcc, v137, v122
	v_mul_f32_e32 v136, v136, v147
	s_and_b64 s[42:43], s[16:17], vcc
	v_cndmask_b32_e64 v147, v136, 0, s[42:43]
	v_add_u32_e32 v136, 0x50, v160
	v_mul_f32_e32 v137, v110, v135
	v_cmp_gt_i32_e32 vcc, v136, v122
	v_mul_f32_e32 v137, v137, v148
	s_and_b64 s[42:43], s[16:17], vcc
	v_cndmask_b32_e64 v148, v137, 0, s[42:43]
	v_add_u32_e32 v137, 0x51, v160
	v_mul_f32_e32 v136, v111, v135
	v_cmp_gt_i32_e32 vcc, v137, v122
	v_mul_f32_e32 v136, v136, v149
	s_and_b64 s[42:43], s[16:17], vcc
	v_add_u32_e32 v137, 0x52, v160
	v_cndmask_b32_e64 v149, v136, 0, s[42:43]
	v_mul_f32_e32 v136, v112, v135
	v_cmp_gt_i32_e32 vcc, v137, v122
	v_mul_f32_e32 v136, v136, v150
	s_and_b64 s[42:43], s[16:17], vcc
	v_add_u32_e32 v137, 0x53, v160
	v_cndmask_b32_e64 v150, v136, 0, s[42:43]
	v_mul_f32_e32 v136, v113, v135
	v_cmp_gt_i32_e32 vcc, v137, v122
	v_mul_f32_e32 v136, v136, v151
	s_and_b64 s[42:43], s[16:17], vcc
	v_cndmask_b32_e64 v151, v136, 0, s[42:43]
	v_add_u32_e32 v136, 0x60, v160
	v_mul_f32_e32 v137, v114, v135
	v_cmp_gt_i32_e32 vcc, v136, v122
	v_mul_f32_e32 v137, v137, v152
	s_and_b64 s[42:43], s[16:17], vcc
	v_cndmask_b32_e64 v152, v137, 0, s[42:43]
	v_add_u32_e32 v137, 0x61, v160
	v_mul_f32_e32 v136, v115, v135
	v_cmp_gt_i32_e32 vcc, v137, v122
	v_mul_f32_e32 v136, v136, v153
	s_and_b64 s[42:43], s[16:17], vcc
	v_add_u32_e32 v137, 0x62, v160
	v_cndmask_b32_e64 v153, v136, 0, s[42:43]
	v_mul_f32_e32 v136, v116, v135
	v_cmp_gt_i32_e32 vcc, v137, v122
	v_mul_f32_e32 v136, v136, v154
	s_and_b64 s[42:43], s[16:17], vcc
	v_add_u32_e32 v137, 0x63, v160
	v_cndmask_b32_e64 v154, v136, 0, s[42:43]
	v_mul_f32_e32 v136, v117, v135
	v_cmp_gt_i32_e32 vcc, v137, v122
	v_mul_f32_e32 v136, v136, v155
	s_and_b64 s[42:43], s[16:17], vcc
	v_cndmask_b32_e64 v155, v136, 0, s[42:43]
	v_add_u32_e32 v136, 0x70, v160
	v_mul_f32_e32 v137, v118, v135
	v_cmp_gt_i32_e32 vcc, v136, v122
	v_mul_f32_e32 v137, v137, v156
	s_and_b64 s[42:43], s[16:17], vcc
	v_cndmask_b32_e64 v156, v137, 0, s[42:43]
	v_add_u32_e32 v137, 0x71, v160
	v_mul_f32_e32 v136, v119, v135
	v_cmp_gt_i32_e32 vcc, v137, v122
	v_mul_f32_e32 v136, v136, v157
	s_and_b64 s[42:43], s[16:17], vcc
	v_add_u32_e32 v137, 0x72, v160
	v_cndmask_b32_e64 v157, v136, 0, s[42:43]
	v_mul_f32_e32 v136, v120, v135
	v_cmp_gt_i32_e32 vcc, v137, v122
	v_mul_f32_e32 v136, v136, v158
	s_and_b64 s[42:43], s[16:17], vcc
	v_cndmask_b32_e64 v158, v136, 0, s[42:43]
	v_add_u32_e32 v136, 0x73, v160
	v_mul_f32_e32 v135, v121, v135
	v_cmp_gt_i32_e32 vcc, v136, v122
	v_mul_f32_e32 v135, v135, v159
	s_and_b64 s[16:17], s[16:17], vcc
	v_cndmask_b32_e64 v135, v135, 0, s[16:17]
	v_cvt_pk_bf16_f32 v136, v66, v67
	v_cvt_pk_bf16_f32 v137, v68, v69
	v_cvt_pk_bf16_f32 v138, v70, v71
	v_cvt_pk_bf16_f32 v139, v72, v73
	v_cvt_pk_bf16_f32 v140, v161, v162
	v_cvt_pk_bf16_f32 v141, v163, v164
	v_cvt_pk_bf16_f32 v142, v165, v166
	v_cvt_pk_bf16_f32 v143, v167, v143
	v_cvt_pk_bf16_f32 v70, v144, v145
	v_cvt_pk_bf16_f32 v71, v146, v147
	v_cvt_pk_bf16_f32 v72, v148, v149
	v_cvt_pk_bf16_f32 v73, v150, v151
	v_cvt_pk_bf16_f32 v66, v152, v153
	v_cvt_pk_bf16_f32 v67, v154, v155
	v_cvt_pk_bf16_f32 v68, v156, v157
	v_cvt_pk_bf16_f32 v69, v158, v135
	v_add3_u32 v135, s40, v87, v127
	v_add_u32_e32 v176, 0x4800, v135
	v_add_u32_e32 v177, 0x5800, v135
	v_add_u32_e32 v178, 0x6800, v135
	v_add_u32_e32 v179, 0x7800, v135
	v_add_u32_e32 v180, 0x8800, v135
	v_add_u32_e32 v181, 0x9800, v135
	v_add_u32_e32 v182, 0xa800, v135
	v_add_u32_e32 v135, 0xb800, v135
	ds_read_b64 v[144:145], v176
	ds_read_b64 v[146:147], v176 offset:32
	ds_read_b64 v[148:149], v177 offset:256
	ds_read_b64 v[150:151], v177 offset:288
	ds_read_b64 v[152:153], v178 offset:512
	ds_read_b64 v[154:155], v178 offset:544
	ds_read_b64 v[156:157], v179 offset:768
	ds_read_b64 v[158:159], v179 offset:800
	ds_read_b64 v[160:161], v180 offset:1024
	ds_read_b64 v[162:163], v180 offset:1056
	ds_read_b64 v[164:165], v181 offset:1280
	ds_read_b64 v[166:167], v181 offset:1312
	ds_read_b64 v[168:169], v182 offset:1536
	ds_read_b64 v[170:171], v182 offset:1568
	ds_read_b64 v[172:173], v135 offset:1792
	ds_read_b64 v[174:175], v135 offset:1824
	s_waitcnt lgkmcnt(14)
; template <int D, int DV, int MODE, int NMAP, int KT> ...
;     ...
;                 for (int b_ = 0; b_ < NVB; ++b_) {
;                     if (b_ + 1 < NVB) AT_VLOAD(b_ + 1, (b_ + 1) & 1);
;                     __builtin_amdgcn_sched_barrier(0);
;                     const int kk_ = b_ / NCB, c0_ = (b_ % NCB) * CBB;
;                     __builtin_amdgcn_s_setprio(1);
; #pragma unroll
;                     for (int x_ = 0; x_ < CBB; ++x_)
; #pragma unroll
;                         for (int mp = 0; mp < NMAP; ++mp) o[mp][c0_ + x_] = __builtin_amdgcn_mfma_f32_16x16x32_bf16(vfr[b_ & 1][x_], pb[mp][kk_], o[mp][c0_ + x_], 0, 0, 0);
;                     __builtin_amdgcn_s_setprio(0);
;                     __builtin_amdgcn_sched_barrier(0);
;                 }
	v_mfma_f32_16x16x32_bf16 v[30:33], v[144:147], v[136:139], v[30:33]
	s_waitcnt lgkmcnt(12)
	v_mfma_f32_16x16x32_bf16 v[26:29], v[148:151], v[136:139], v[26:29]
	s_waitcnt lgkmcnt(10)
	v_mfma_f32_16x16x32_bf16 v[22:25], v[152:155], v[136:139], v[22:25]
	s_waitcnt lgkmcnt(8)
	v_mfma_f32_16x16x32_bf16 v[18:21], v[156:159], v[136:139], v[18:21]
	ds_read_b64 v[144:145], v176 offset:64
	ds_read_b64 v[146:147], v176 offset:96
	ds_read_b64 v[148:149], v177 offset:320
	ds_read_b64 v[150:151], v177 offset:352
	ds_read_b64 v[152:153], v178 offset:576
	ds_read_b64 v[154:155], v178 offset:608
	ds_read_b64 v[156:157], v179 offset:832
	ds_read_b64 v[158:159], v179 offset:864
	s_waitcnt lgkmcnt(14)
	v_mfma_f32_16x16x32_bf16 v[14:17], v[160:163], v[136:139], v[14:17]
	s_waitcnt lgkmcnt(12)
	v_mfma_f32_16x16x32_bf16 v[10:13], v[164:167], v[136:139], v[10:13]
	s_waitcnt lgkmcnt(10)
	v_mfma_f32_16x16x32_bf16 v[6:9], v[168:171], v[136:139], v[6:9]
	s_waitcnt lgkmcnt(8)
	v_mfma_f32_16x16x32_bf16 v[2:5], v[172:175], v[136:139], v[2:5]
	ds_read_b64 v[136:137], v180 offset:1088
	ds_read_b64 v[138:139], v180 offset:1120
	ds_read_b64 v[160:161], v181 offset:1344
	ds_read_b64 v[162:163], v181 offset:1376
	ds_read_b64 v[164:165], v182 offset:1600
	ds_read_b64 v[166:167], v182 offset:1632
	ds_read_b64 v[168:169], v135 offset:1856
	ds_read_b64 v[170:171], v135 offset:1888
	s_waitcnt lgkmcnt(14)
	v_mfma_f32_16x16x32_bf16 v[30:33], v[144:147], v[140:143], v[30:33]
	s_waitcnt lgkmcnt(12)
	v_mfma_f32_16x16x32_bf16 v[26:29], v[148:151], v[140:143], v[26:29]
	s_waitcnt lgkmcnt(10)
	v_mfma_f32_16x16x32_bf16 v[22:25], v[152:155], v[140:143], v[22:25]
	s_waitcnt lgkmcnt(8)
	v_mfma_f32_16x16x32_bf16 v[18:21], v[156:159], v[140:143], v[18:21]
	ds_read_b64 v[144:145], v176 offset:128
	ds_read_b64 v[146:147], v176 offset:160
	ds_read_b64 v[148:149], v177 offset:384
	ds_read_b64 v[150:151], v177 offset:416
	ds_read_b64 v[152:153], v178 offset:640
	ds_read_b64 v[154:155], v178 offset:672
	ds_read_b64 v[156:157], v179 offset:896
	ds_read_b64 v[158:159], v179 offset:928
	s_waitcnt lgkmcnt(14)
	v_mfma_f32_16x16x32_bf16 v[14:17], v[136:139], v[140:143], v[14:17]
	s_waitcnt lgkmcnt(12)
	v_mfma_f32_16x16x32_bf16 v[10:13], v[160:163], v[140:143], v[10:13]
	s_waitcnt lgkmcnt(10)
	v_mfma_f32_16x16x32_bf16 v[6:9], v[164:167], v[140:143], v[6:9]
	s_waitcnt lgkmcnt(8)
	v_mfma_f32_16x16x32_bf16 v[2:5], v[168:171], v[140:143], v[2:5]
	ds_read_b64 v[136:137], v180 offset:1152
	ds_read_b64 v[138:139], v180 offset:1184
	ds_read_b64 v[140:141], v181 offset:1408
	ds_read_b64 v[142:143], v181 offset:1440
	ds_read_b64 v[160:161], v182 offset:1664
	ds_read_b64 v[162:163], v182 offset:1696
	ds_read_b64 v[164:165], v135 offset:1920
	ds_read_b64 v[166:167], v135 offset:1952
	s_waitcnt lgkmcnt(14)
	v_mfma_f32_16x16x32_bf16 v[30:33], v[144:147], v[70:73], v[30:33]
	s_waitcnt lgkmcnt(12)
	v_mfma_f32_16x16x32_bf16 v[26:29], v[148:151], v[70:73], v[26:29]
	s_waitcnt lgkmcnt(10)
	v_mfma_f32_16x16x32_bf16 v[22:25], v[152:155], v[70:73], v[22:25]
	s_waitcnt lgkmcnt(8)
	v_mfma_f32_16x16x32_bf16 v[18:21], v[156:159], v[70:73], v[18:21]
	ds_read_b64 v[144:145], v176 offset:192
	ds_read_b64 v[146:147], v176 offset:224
	ds_read_b64 v[148:149], v177 offset:448
	ds_read_b64 v[150:151], v177 offset:480
	ds_read_b64 v[152:153], v178 offset:704
	ds_read_b64 v[154:155], v178 offset:736
	ds_read_b64 v[156:157], v179 offset:960
	ds_read_b64 v[158:159], v179 offset:992
	s_waitcnt lgkmcnt(14)
	v_mfma_f32_16x16x32_bf16 v[14:17], v[136:139], v[70:73], v[14:17]
	s_waitcnt lgkmcnt(12)
	v_mfma_f32_16x16x32_bf16 v[10:13], v[140:143], v[70:73], v[10:13]
	s_waitcnt lgkmcnt(10)
	v_mfma_f32_16x16x32_bf16 v[6:9], v[160:163], v[70:73], v[6:9]
	s_waitcnt lgkmcnt(8)
	v_mfma_f32_16x16x32_bf16 v[2:5], v[164:167], v[70:73], v[2:5]
	ds_read_b64 v[70:71], v180 offset:1216
	ds_read_b64 v[72:73], v180 offset:1248
	ds_read_b64 v[136:137], v181 offset:1472
	ds_read_b64 v[138:139], v181 offset:1504
	ds_read_b64 v[140:141], v182 offset:1728
	ds_read_b64 v[142:143], v182 offset:1760
	ds_read_b64 v[160:161], v135 offset:1984
	ds_read_b64 v[162:163], v135 offset:2016
	s_waitcnt lgkmcnt(14)
	v_mfma_f32_16x16x32_bf16 v[30:33], v[144:147], v[66:69], v[30:33]
	s_waitcnt lgkmcnt(12)
	v_mfma_f32_16x16x32_bf16 v[26:29], v[148:151], v[66:69], v[26:29]
	s_waitcnt lgkmcnt(10)
	v_mfma_f32_16x16x32_bf16 v[22:25], v[152:155], v[66:69], v[22:25]
	s_waitcnt lgkmcnt(8)
	v_mfma_f32_16x16x32_bf16 v[18:21], v[156:159], v[66:69], v[18:21]
	s_waitcnt lgkmcnt(6)
	v_mfma_f32_16x16x32_bf16 v[14:17], v[70:73], v[66:69], v[14:17]
	s_waitcnt lgkmcnt(4)
	v_mfma_f32_16x16x32_bf16 v[10:13], v[136:139], v[66:69], v[10:13]
	s_waitcnt lgkmcnt(2)
	v_mfma_f32_16x16x32_bf16 v[6:9], v[140:143], v[66:69], v[6:9]
	s_waitcnt lgkmcnt(0)
	v_mfma_f32_16x16x32_bf16 v[2:5], v[160:163], v[66:69], v[2:5]

; template <class Epi, class Sched, bool ALIGN_EPI = false, bool SP2 = false>
; __device__ __forceinline__ void gemm_phase(PG8_LAS unsigned char* lds, const Gemm g, const Sched& S, const Epi& E) {
;     int tid_ = threadIdx.x; asm volatile("" : "+v"(tid_)); const int tid = tid_, wid = __builtin_amdgcn_readfirstlane(tid >> 6), lane = tid & 63, wr = wid >> 2, wc = wid & 3, fr = lane & 15, fq = lane >> 4;
;     const bf16_t* gA_ = g.A; const bf16_t* gB_ = g.Bt; int K = g.K; asm volatile("" : "+s"(gA_), "+s"(gB_), "+s"(K)); const int nt = K / BK;
;     unsigned voffA[2], voffB[2];
; #pragma unroll
;     for (int i = 0; i < 2; ++i) { int R, C; stage_rc(tid * 16 + i * 8192, R, C); const int Rb = Epi::PERM ? ((R & ~31) + perm32(R & 31)) : R;
;         voffA[i] = (unsigned)(R * K + C) * 2u; voffB[i] = (unsigned)(Rb * K + C) * 2u; }
;     const size_t kstep = (size_t)(BK * 2);
;     const size_t hstep = (size_t)HALF * K * 2;
;     const size_t tstep = 2 * hstep;
;     const unsigned ldsw = (unsigned)wid * 1024u;
;     const int aoff = lds_byte(wr * 64 + fr, fq * 8), boff = lds_byte(wc * 32 + fr, fq * 8);
;     ...
;     Unit cur, nxt; int ui = 0;
;     if (!S.next(0, cur)) return;
; __global__ void __launch_bounds__(512, 2) mega_fwd(Params P) {
;     ...
;                     __syncthreads();
;                     { PHASE_IDS(); pg8::Gemm g{Z5, Wl + OFF_WEX, T_TOK, 512, 512}; pg8::StaticOrder S; S.init(T_TOK, 512, G, blk);
;                       pg8::EpiGlu E{CAT, 1024, Z5, P.in[30] + (size_t)hl * 512};
;                       pg8::gemm_phase<pg8::EpiGlu, pg8::StaticOrder, true, true>(lds, g, S, E); }
.LBB0_799:
	s_setprio 0
	v_readlane_b32 s2, v254, 7
	v_readlane_b32 s8, v254, 3
	v_readlane_b32 s3, v254, 8
	v_readlane_b32 s9, v254, 4
	v_readlane_b32 s10, v254, 5
	v_readlane_b32 s11, v254, 6
	v_mov_b32_e32 v0, v211
	v_readlane_b32 s33, v254, 0
	s_mov_b32 s34, s2
	s_mov_b64 s[4:5], s[10:11]
	s_mov_b64 s[2:3], s[8:9]
	s_waitcnt lgkmcnt(0)
	s_barrier
	s_add_u32 s6, s4, 0x33800000
	v_readlane_b32 s20, v255, 35
	s_addc_u32 s7, s5, 0
	s_mul_i32 s2, s20, 0x3100000
	s_mul_hi_i32 s1, s20, 0x3100000
	s_add_u32 s2, s4, s2
	s_addc_u32 s1, s5, s1
	s_add_u32 s8, s2, 0x3200000
	s_addc_u32 s9, s1, 0
	v_mov_b32_e32 v19, v211
	s_mov_b64 s[10:11], s[6:7]
	v_readfirstlane_b32 s24, v19
	s_movk_i32 s2, 0x200
	s_cmpk_gt_i32 s33, 0x1ff
	s_mov_b64 s[42:43], 0x800
	s_cbranch_scc1 .LBB0_829
	s_ashr_i32 s40, s33, 31
	s_lshr_b32 s1, s40, 29
	s_add_i32 s14, s33, s1
	s_and_b32 s1, s14, -8
	s_sub_i32 s3, s33, s1
	s_cmp_gt_i32 s3, -1
	s_mov_b64 s[12:13], -1
	s_cbranch_scc0 .LBB0_802
	s_lshl_b32 s1, s3, 6
	s_mov_b64 s[12:13], 0

; #define LAS __attribute__((address_space(3)))
; #define AT_SLOAD(bi_, sl_) do { _Pragma("unroll") for (int x_ = 0; x_ < NBB; ++x_) _Pragma("unroll") for (int kk = 0; kk < KD; ++kk) \
;                     kfr[sl_][x_][kk] = *(const LAS bf16x8*)(Ks + (((bi_) * NBB + x_) * 16 + r) * KSTR + mp * D + kk * 32 + g4 * 8); } while (0)
; template <int D, int DV, int MODE, int NMAP, int KT> ...
;     ...
;         if (MODE == 0 || kt * KT <= rowmin + 15) {
;             const LAS bf16_t* Ks = (const LAS bf16_t*)(lds + cur); const LAS bf16_t* Vt = (const LAS bf16_t*)(lds + cur + KS_BYTES);
;             const bool diag = (MODE != 0) && (kt * KT + KT - 1 > rowmin);
;             bf16x8 pb[NMAP][KK2];
;             f32x4 sall[NMAP][NB];
; #pragma unroll
;             for (int mp = 0; mp < NMAP; ++mp) {
;                 f32x4 (&s)[NB] = sall[mp];
;                 constexpr int KD = D / 32, NBB = (KD >= 8) ? 1 : (8 / KD), NSB = NB / NBB;
;                 bf16x8 kfr[2][NBB][KD];
;     ...
;                 AT_SLOAD(0, 0);
; #pragma unroll
;                 for (int bi = 0; bi < NSB; ++bi) {
;                     if (bi + 1 < NSB) AT_SLOAD(bi + 1, (bi + 1) & 1);
;                     __builtin_amdgcn_sched_barrier(0);
;                     __builtin_amdgcn_s_setprio(1);
; #pragma unroll
;                     for (int x_ = 0; x_ < NBB; ++x_) { const int nb = bi * NBB + x_;
;                         s[nb] = __builtin_amdgcn_mfma_f32_16x16x32_bf16(kfr[bi & 1][x_][0], qf[mp][0], (f32x4){0.f, 0.f, 0.f, 0.f}, 0, 0, 0);
; #pragma unroll
;                         for (int kk = 1; kk < KD; ++kk) s[nb] = __builtin_amdgcn_mfma_f32_16x16x32_bf16(kfr[bi & 1][x_][kk], qf[mp][kk], s[nb], 0, 0, 0); }
;                     __builtin_amdgcn_s_setprio(0);
;                     __builtin_amdgcn_sched_barrier(0);
;                 }
;     ...
;             }
; #pragma unroll
;             for (int mp = 0; mp < NMAP; ++mp) {
;                 f32x4 (&s)[NB] = sall[mp];
;                 if (MODE < 2) {
;                     if (diag) {
; #pragma unroll
;                         for (int nb = 0; nb < NB; ++nb)
; #pragma unroll
;                             for (int j = 0; j < 4; ++j) { if (kt * KT + nb * 16 + g4 * 4 + j > myrow) s[nb][j] = -INFINITY; }
.LBB0_1096:
	s_cmp_gt_i32 s76, s75
	s_cbranch_scc1 .LBB0_1106
	s_bitcmp1_b32 s2, 0
	s_cselect_b32 s2, 0x8c00, 0
	s_add_i32 s83, s2, 0
	v_lshlrev_b32_e32 v98, 1, v148
	v_add3_u32 v174, s83, v98, v151
	ds_read_b128 v[98:101], v174
	ds_read_b128 v[102:105], v174 offset:64
	ds_read_b128 v[106:109], v174 offset:4352
	ds_read_b128 v[110:113], v174 offset:4416
	ds_read_b128 v[114:117], v174 offset:8704
	ds_read_b128 v[118:121], v174 offset:8768
	ds_read_b128 v[158:161], v174 offset:13056
	ds_read_b128 v[162:165], v174 offset:13120
	s_add_i32 s2, s76, 63
	s_waitcnt lgkmcnt(7)
	v_mfma_f32_16x16x32_bf16 v[98:101], v[98:101], v[2:5], 0
	s_waitcnt lgkmcnt(6)
	v_mfma_f32_16x16x32_bf16 v[126:129], v[102:105], v[6:9], v[98:101]
	s_waitcnt lgkmcnt(5)
	v_mfma_f32_16x16x32_bf16 v[98:101], v[106:109], v[2:5], 0
	s_waitcnt lgkmcnt(4)
	v_mfma_f32_16x16x32_bf16 v[122:125], v[110:113], v[6:9], v[98:101]
	s_waitcnt lgkmcnt(3)
	v_mfma_f32_16x16x32_bf16 v[98:101], v[114:117], v[2:5], 0
	s_waitcnt lgkmcnt(2)
	v_mfma_f32_16x16x32_bf16 v[118:121], v[118:121], v[6:9], v[98:101]
	s_waitcnt lgkmcnt(1)
	v_mfma_f32_16x16x32_bf16 v[98:101], v[158:161], v[2:5], 0
	s_waitcnt lgkmcnt(0)
	v_mfma_f32_16x16x32_bf16 v[106:109], v[162:165], v[6:9], v[98:101]
	s_nop 5
	ds_read_b128 v[98:101], v174 offset:128
	ds_read_b128 v[102:105], v174 offset:192
	ds_read_b128 v[110:113], v174 offset:4480
	ds_read_b128 v[158:161], v174 offset:4544
	ds_read_b128 v[162:165], v174 offset:8832
	ds_read_b128 v[166:169], v174 offset:8896
	ds_read_b128 v[170:173], v174 offset:13184
	ds_read_b128 v[174:177], v174 offset:13248
	s_waitcnt lgkmcnt(7)
	v_mfma_f32_16x16x32_bf16 v[98:101], v[98:101], v[10:13], 0
	s_waitcnt lgkmcnt(6)
	v_mfma_f32_16x16x32_bf16 v[114:117], v[102:105], v[14:17], v[98:101]
	s_waitcnt lgkmcnt(5)
	v_mfma_f32_16x16x32_bf16 v[98:101], v[110:113], v[10:13], 0
	s_waitcnt lgkmcnt(4)
	v_mfma_f32_16x16x32_bf16 v[110:113], v[158:161], v[14:17], v[98:101]
	s_waitcnt lgkmcnt(3)
	v_mfma_f32_16x16x32_bf16 v[98:101], v[162:165], v[10:13], 0
	s_waitcnt lgkmcnt(2)
	v_mfma_f32_16x16x32_bf16 v[102:105], v[166:169], v[14:17], v[98:101]
	s_waitcnt lgkmcnt(1)
	v_mfma_f32_16x16x32_bf16 v[98:101], v[170:173], v[10:13], 0
	s_waitcnt lgkmcnt(0)
	v_mfma_f32_16x16x32_bf16 v[98:101], v[174:177], v[14:17], v[98:101]
	v_add_u32_e32 v171, s76, v150
	s_cmp_gt_i32 s2, s74
	v_add_u32_e32 v172, 2, v171
	v_add_u32_e32 v170, 3, v171
	v_add_u32_e32 v169, 16, v171
	v_add_u32_e32 v168, 17, v171
	v_add_u32_e32 v167, 18, v171
	v_add_u32_e32 v166, 19, v171
	v_add_u32_e32 v165, 32, v171
	v_add_u32_e32 v164, 33, v171
	v_add_u32_e32 v163, 34, v171
	v_add_u32_e32 v162, 35, v171
	v_add_u32_e32 v161, 48, v171
	v_add_u32_e32 v160, 49, v171
	v_add_u32_e32 v159, 50, v171
	v_add_u32_e32 v158, 51, v171
	s_cselect_b64 s[52:53], -1, 0
	s_cmp_le_i32 s2, s74
	v_cmp_gt_i32_e64 s[10:11], v171, v149
	v_cmp_lt_i32_e64 s[8:9], v171, v149
	v_cmp_le_i32_e64 s[28:29], v172, v149
	v_cmp_le_i32_e64 s[30:31], v170, v149
	v_cmp_gt_i32_e64 s[20:21], v169, v149
	v_cmp_le_i32_e64 s[22:23], v168, v149
	v_cmp_le_i32_e64 s[24:25], v167, v149
	v_cmp_le_i32_e64 s[26:27], v166, v149
	v_cmp_gt_i32_e64 s[12:13], v165, v149
	v_cmp_le_i32_e64 s[14:15], v164, v149
	v_cmp_le_i32_e64 s[16:17], v163, v149
	v_cmp_le_i32_e64 s[18:19], v162, v149
	v_cmp_gt_i32_e32 vcc, v161, v149
	v_cmp_le_i32_e64 s[2:3], v160, v149
	v_cmp_le_i32_e64 s[4:5], v159, v149
	v_cmp_le_i32_e64 s[6:7], v158, v149
	s_cbranch_scc1 .LBB0_1099
	v_mov_b32_e32 v174, s70
	v_cndmask_b32_e64 v173, v126, v174, s[10:11]
	v_cndmask_b32_e64 v126, v173, v126, s[8:9]
	v_cndmask_b32_e64 v127, v225, v127, s[8:9]
	v_cndmask_b32_e64 v128, v225, v128, s[28:29]
	v_cndmask_b32_e64 v129, v225, v129, s[30:31]
	v_cndmask_b32_e64 v122, v122, v174, s[20:21]
	v_cndmask_b32_e64 v123, v225, v123, s[22:23]
	v_cndmask_b32_e64 v124, v225, v124, s[24:25]
	v_cndmask_b32_e64 v125, v225, v125, s[26:27]
	v_cndmask_b32_e64 v118, v118, v174, s[12:13]
	v_cndmask_b32_e64 v119, v225, v119, s[14:15]
	v_cndmask_b32_e64 v120, v225, v120, s[16:17]
	v_cndmask_b32_e64 v121, v225, v121, s[18:19]
	v_cndmask_b32_e32 v106, v106, v174, vcc
	v_cndmask_b32_e64 v107, v225, v107, s[2:3]
	v_cndmask_b32_e64 v108, v225, v108, s[4:5]
	v_cndmask_b32_e64 v109, v225, v109, s[6:7]

; __device__ __forceinline__ unsigned cvt_pk_bf16(float lo, float hi) { unsigned r; asm volatile("v_cvt_pk_bf16_f32 %0, %1, %2" : "=v"(r) : "v"(lo), "v"(hi)); return r; }
; template <int D, int DV, int MODE, int NMAP, int KT> ...
;     ...
;                     const float nm = -m[mp]; float ps = 0.f;
; #pragma unroll
;                     for (int nb = 0; nb < NB; ++nb)
; #pragma unroll
;                         for (int j = 0; j < 4; ++j) { const float p = __builtin_amdgcn_exp2f(fmaf(s[nb][j], sc, nm)); ps += p; s[nb][j] = p; }
;                     l[mp] += ps;
;                 } else {
;                     const float rowf = __builtin_amdgcn_exp2f(l2g * (float)(myrow - kt * KT));
; #pragma unroll
;                     for (int nb = 0; nb < NB; ++nb)
; #pragma unroll
;                         for (int j = 0; j < 4; ++j) { float p = s[nb][j] * (rowf * ck[nb][j]); if (diag && (kt * KT + nb * 16 + g4 * 4 + j > myrow)) p = 0.f; s[nb][j] = p; }
;                 }
; #pragma unroll
;                 for (int kk = 0; kk < KK2; ++kk) { u32x4 wv; wv.x = cvt_pk_bf16(s[2 * kk][0], s[2 * kk][1]); wv.y = cvt_pk_bf16(s[2 * kk][2], s[2 * kk][3]);
;                     wv.z = cvt_pk_bf16(s[2 * kk + 1][0], s[2 * kk + 1][1]); wv.w = cvt_pk_bf16(s[2 * kk + 1][2], s[2 * kk + 1][3]); pb[mp][kk] = __builtin_bit_cast(bf16x8, wv); }
;             }
;             {
;                 constexpr int CBB = 4, NCB = (DV / 16) / CBB, NVB = KK2 * NCB;
;                 bf16x8 vfr[2][CBB];
;     ...
;                 AT_VLOAD(0, 0);
; #pragma unroll
;                 for (int b_ = 0; b_ < NVB; ++b_) {
;                     if (b_ + 1 < NVB) AT_VLOAD(b_ + 1, (b_ + 1) & 1);
;                     __builtin_amdgcn_sched_barrier(0);
;                     const int kk_ = b_ / NCB, c0_ = (b_ % NCB) * CBB;
;                     __builtin_amdgcn_s_setprio(1);
; #pragma unroll
;                     for (int x_ = 0; x_ < CBB; ++x_)
; #pragma unroll
;                         for (int mp = 0; mp < NMAP; ++mp) o[mp][c0_ + x_] = __builtin_amdgcn_mfma_f32_16x16x32_bf16(vfr[b_ & 1][x_], pb[mp][kk_], o[mp][c0_ + x_], 0, 0, 0);
;                     __builtin_amdgcn_s_setprio(0);
;                     __builtin_amdgcn_sched_barrier(0);
;                 }
.LBB0_1105:
	v_fma_f32 v114, v114, s71, -v0
	v_exp_f32_e32 v114, v114
	v_fma_f32 v115, v115, s71, -v0
	v_exp_f32_e32 v115, v115
	v_fma_f32 v116, v116, s71, -v0
	v_exp_f32_e32 v116, v116
	v_fma_f32 v117, v117, s71, -v0
	v_exp_f32_e32 v117, v117
	v_fma_f32 v110, v110, s71, -v0
	v_add_f32_e32 v122, 0, v114
	v_exp_f32_e32 v110, v110
	v_fma_f32 v111, v111, s71, -v0
	v_add_f32_e32 v122, v115, v122
	v_exp_f32_e32 v111, v111
	v_fma_f32 v112, v112, s71, -v0
	v_add_f32_e32 v122, v116, v122
	v_exp_f32_e32 v112, v112
	v_fma_f32 v113, v113, s71, -v0
	v_add_f32_e32 v122, v117, v122
	v_exp_f32_e32 v113, v113
	v_fma_f32 v102, v102, s71, -v0
	v_add_f32_e32 v122, v110, v122
	v_exp_f32_e32 v102, v102
	v_fma_f32 v103, v103, s71, -v0
	v_add_f32_e32 v122, v111, v122
	v_exp_f32_e32 v103, v103
	v_fma_f32 v104, v104, s71, -v0
	v_add_f32_e32 v122, v112, v122
	v_exp_f32_e32 v104, v104
	v_fma_f32 v105, v105, s71, -v0
	v_add_f32_e32 v122, v113, v122
	v_exp_f32_e32 v105, v105
	v_fma_f32 v98, v98, s71, -v0
	v_add_f32_e32 v122, v102, v122
	v_exp_f32_e32 v123, v98
	v_add_f32_e32 v122, v103, v122
	v_add_f32_e32 v122, v104, v122
	v_add_f32_e32 v122, v105, v122
	v_fma_f32 v99, v99, s71, -v0
	v_add_f32_e32 v98, v123, v122
	v_exp_f32_e32 v122, v99
	v_fma_f32 v99, v100, s71, -v0
	v_exp_f32_e32 v124, v99
	v_fma_f32 v99, v101, s71, -v0
	v_exp_f32_e32 v125, v99
	v_add_f32_e32 v98, v122, v98
	v_add_f32_e32 v98, v124, v98
	v_add3_u32 v170, s83, v148, v152
	v_add_f32_e32 v98, v125, v98
	v_add_u32_e32 v174, 0x4000, v170
	v_add_u32_e32 v175, 0x4800, v170
	v_add_u32_e32 v176, 0x5000, v170
	v_add_u32_e32 v177, 0x5800, v170
	v_add_u32_e32 v178, 0x6800, v170
	v_add_u32_e32 v179, 0x7000, v170
	v_add_u32_e32 v180, 0x7800, v170
	v_add_u32_e32 v181, 0x8000, v170
	v_add_f32_e32 v137, v137, v98
	v_cvt_pk_bf16_f32 v98, v114, v115
	v_cvt_pk_bf16_f32 v99, v116, v117
	v_cvt_pk_bf16_f32 v100, v110, v111
	v_cvt_pk_bf16_f32 v101, v112, v113
	v_cvt_pk_bf16_f32 v102, v102, v103
	v_cvt_pk_bf16_f32 v103, v104, v105
	v_cvt_pk_bf16_f32 v104, v123, v122
	v_cvt_pk_bf16_f32 v105, v124, v125
	ds_read_b64 v[110:111], v174 offset:1024
	ds_read_b64 v[112:113], v174 offset:1056
	ds_read_b64 v[114:115], v175 offset:1280
	ds_read_b64 v[116:117], v175 offset:1312
	ds_read_b64 v[122:123], v176 offset:1536
	ds_read_b64 v[124:125], v176 offset:1568
	ds_read_b64 v[126:127], v177 offset:1792
	ds_read_b64 v[128:129], v177 offset:1824
	ds_read_b64 v[158:159], v178
	ds_read_b64 v[160:161], v178 offset:32
	ds_read_b64 v[162:163], v179 offset:256
	ds_read_b64 v[164:165], v179 offset:288
	ds_read_b64 v[166:167], v180 offset:512
	ds_read_b64 v[168:169], v180 offset:544
	ds_read_b64 v[170:171], v181 offset:768
	ds_read_b64 v[172:173], v181 offset:800
	s_waitcnt lgkmcnt(14)
	v_mfma_f32_16x16x32_bf16 v[90:93], v[110:113], v[118:121], v[90:93]
	v_mfma_f32_16x16x32_bf16 v[94:97], v[110:113], v[98:101], v[94:97]
	s_waitcnt lgkmcnt(12)
	v_mfma_f32_16x16x32_bf16 v[82:85], v[114:117], v[118:121], v[82:85]
	v_mfma_f32_16x16x32_bf16 v[86:89], v[114:117], v[98:101], v[86:89]
	s_waitcnt lgkmcnt(10)
	v_mfma_f32_16x16x32_bf16 v[74:77], v[122:125], v[118:121], v[74:77]
	v_mfma_f32_16x16x32_bf16 v[78:81], v[122:125], v[98:101], v[78:81]
	s_waitcnt lgkmcnt(8)
	v_mfma_f32_16x16x32_bf16 v[66:69], v[126:129], v[118:121], v[66:69]
	v_mfma_f32_16x16x32_bf16 v[70:73], v[126:129], v[98:101], v[70:73]
	ds_read_b64 v[110:111], v174 offset:1088
	ds_read_b64 v[112:113], v174 offset:1120
	ds_read_b64 v[114:115], v175 offset:1344
	ds_read_b64 v[116:117], v175 offset:1376
	ds_read_b64 v[122:123], v176 offset:1600
	ds_read_b64 v[124:125], v176 offset:1632
	ds_read_b64 v[126:127], v177 offset:1856
	ds_read_b64 v[128:129], v177 offset:1888
	s_waitcnt lgkmcnt(14)
	v_mfma_f32_16x16x32_bf16 v[50:53], v[158:161], v[118:121], v[50:53]
	v_mfma_f32_16x16x32_bf16 v[54:57], v[158:161], v[98:101], v[54:57]
	s_waitcnt lgkmcnt(12)
	v_mfma_f32_16x16x32_bf16 v[42:45], v[162:165], v[118:121], v[42:45]
	v_mfma_f32_16x16x32_bf16 v[46:49], v[162:165], v[98:101], v[46:49]
	s_waitcnt lgkmcnt(10)
	v_mfma_f32_16x16x32_bf16 v[34:37], v[166:169], v[118:121], v[34:37]
	v_mfma_f32_16x16x32_bf16 v[38:41], v[166:169], v[98:101], v[38:41]
	s_waitcnt lgkmcnt(8)
	v_mfma_f32_16x16x32_bf16 v[22:25], v[170:173], v[118:121], v[22:25]
	v_mfma_f32_16x16x32_bf16 v[26:29], v[170:173], v[98:101], v[26:29]
	ds_read_b64 v[98:99], v178 offset:64
	ds_read_b64 v[100:101], v178 offset:96
	ds_read_b64 v[118:119], v179 offset:320
	ds_read_b64 v[120:121], v179 offset:352
	ds_read_b64 v[158:159], v180 offset:576
	ds_read_b64 v[160:161], v180 offset:608
	ds_read_b64 v[162:163], v181 offset:832
	ds_read_b64 v[164:165], v181 offset:864
	s_waitcnt lgkmcnt(14)
	v_mfma_f32_16x16x32_bf16 v[90:93], v[110:113], v[106:109], v[90:93]
	v_mfma_f32_16x16x32_bf16 v[94:97], v[110:113], v[102:105], v[94:97]
	s_waitcnt lgkmcnt(12)
	v_mfma_f32_16x16x32_bf16 v[82:85], v[114:117], v[106:109], v[82:85]
	v_mfma_f32_16x16x32_bf16 v[86:89], v[114:117], v[102:105], v[86:89]
	s_waitcnt lgkmcnt(10)
	v_mfma_f32_16x16x32_bf16 v[74:77], v[122:125], v[106:109], v[74:77]
	v_mfma_f32_16x16x32_bf16 v[78:81], v[122:125], v[102:105], v[78:81]
	s_waitcnt lgkmcnt(8)
	v_mfma_f32_16x16x32_bf16 v[66:69], v[126:129], v[106:109], v[66:69]
	v_mfma_f32_16x16x32_bf16 v[70:73], v[126:129], v[102:105], v[70:73]
	s_waitcnt lgkmcnt(6)
	v_mfma_f32_16x16x32_bf16 v[50:53], v[98:101], v[106:109], v[50:53]
	v_mfma_f32_16x16x32_bf16 v[54:57], v[98:101], v[102:105], v[54:57]
	s_waitcnt lgkmcnt(4)
	v_mfma_f32_16x16x32_bf16 v[42:45], v[118:121], v[106:109], v[42:45]
	v_mfma_f32_16x16x32_bf16 v[46:49], v[118:121], v[102:105], v[46:49]
	s_waitcnt lgkmcnt(2)
	v_mfma_f32_16x16x32_bf16 v[34:37], v[158:161], v[106:109], v[34:37]
	v_mfma_f32_16x16x32_bf16 v[38:41], v[158:161], v[102:105], v[38:41]
	s_waitcnt lgkmcnt(0)
	v_mfma_f32_16x16x32_bf16 v[22:25], v[162:165], v[106:109], v[22:25]
	v_mfma_f32_16x16x32_bf16 v[26:29], v[162:165], v[102:105], v[26:29]

; #define LAS __attribute__((address_space(3)))
; __global__ void __launch_bounds__(512, 2) mega_fwd(Params P) {
;     ...
;                     { PHASE_IDS();
;                         LAS float* sA = (LAS float*)lds; LAS float* sB = sA + 32 * 64;
;                         for (int u = blk; u < 256; u += G) {
;                             const int b = u >> 3, cgp = u & 7, jc = tid >> 4, q = tid & 15, ch0 = cgp * 64 + q * 4;
;                             const size_t row0 = (size_t)b * SEQ + jc * 64;
;                             const unsigned* ab = AB + row0 * 512 + ch0;
;                             float h[4] = {0.f, 0.f, 0.f, 0.f}, sl[4] = {0.f, 0.f, 0.f, 0.f};
.LBB0_1109:
	s_setprio 0
	v_readlane_b32 s2, v254, 7
	v_readlane_b32 s4, v254, 3
	v_mov_b32_e32 v0, v211
	v_readlane_b32 s3, v254, 8
	s_mov_b32 s10, s2
	v_readlane_b32 s11, v254, 0
	v_readlane_b32 s6, v254, 5
	v_readlane_b32 s7, v254, 6
	v_readlane_b32 s5, v254, 4
	s_mov_b64 s[2:3], s[6:7]
	v_readlane_b32 s1, v255, 35
	s_cmpk_gt_i32 s11, 0xff
	s_mov_b64 s[42:43], 0x800
	v_readlane_b32 s46, v254, 1
	v_readlane_b32 s47, v254, 2
	s_cbranch_scc1 .LBB0_1120
	v_ashrrev_i32_e32 v118, 4, v0
	v_lshlrev_b32_e32 v2, 6, v118
	v_lshlrev_b32_e32 v0, 2, v0
	v_ashrrev_i32_e32 v3, 31, v2
	v_and_b32_e32 v119, 60, v0
	v_lshlrev_b64 v[74:75], 11, v[2:3]
	v_lshl_add_u32 v120, v119, 2, 0
	v_lshl_add_u64 v[4:5], s[2:3], 0, v[74:75]
	s_mov_b64 s[4:5], 0x33807800
	v_lshl_add_u32 v121, v118, 8, v120
	v_lshl_add_u64 v[76:77], v[4:5], 0, s[4:5]
	s_lshl_b32 s12, s11, 6
	s_lshl_b32 s13, s10, 6
	v_mad_i64_i32 v[78:79], s[4:5], v2, s57, 0
